# attention K/V loop: removed the 6 conservative vmcnt(0) drains right after each next-block LDS-DMA group (prefetch now overlaps the block compute)
# baseline (speedup 1.0000x reference)
; #define LAS __attribute__((address_space(3)))
; __device__ __forceinline__ s16x4 vtr(LAS const unsigned char* p) { return __builtin_bit_cast(s16x4, __builtin_amdgcn_ds_read_tr16_b64_v4i16((LAS v4i16_t*)p)); }
; __device__ __forceinline__ void att_block(const bf16x8 (&kf)[4], const bf16x8 (&qf)[4], const bf16x8 (&va)[4], f32x16& o0, f32x16& o1, float& mrun, float& lrun, bool domask, int lo_, int hi_) {
;     ...
; #pragma unroll
;     for (int i = 0; i < 16; ++i) st[i] = 0.f;
; #pragma unroll
;     for (int kk = 0; kk < 4; ++kk) st = __builtin_amdgcn_mfma_f32_32x32x16_bf16(kf[kk], qf[kk], st, 0, 0, 0);
;     if (domask) {
;         asm volatile("" : "+v"(lo_), "+v"(hi_));
; #pragma unroll
;         for (int i = 0; i < 16; ++i) { const int ci = (i & 3) + 8 * (i >> 2); st[i] = ((ci - lo_) | (hi_ - ci)) < 0 ? -INFINITY : st[i]; }
;     }
;     float bmax = -INFINITY;
; #pragma unroll
;     for (int i = 0; i < 16; ++i) bmax = fmaxf(bmax, st[i]);
;     bmax = fmaxf(bmax, __shfl_xor(bmax, 32));
; __device__ __forceinline__ void att_phase(unsigned char* ws, LAS unsigned char* lds, int lane, int wave, int G) {
;     ...
;             asm volatile("s_waitcnt vmcnt(0)" ::: "memory");
;             if (kb < 5) ATT_DMA_KV(P, kb + 1, sb ^ 1);
;             else if (hn) ATT_DMA_KV(N, 0, sb ^ 1);
;             bf16x8 kf[4], va[4];
; #pragma unroll
;             for (int kk = 0; kk < 4; ++kk) kf[kk] = *(LAS const bf16x8*)(kfb + sb * 4096 + (((2 * kk + h) ^ (qc & 7)) << 4));
;             LAS const unsigned char* trs = trb + 8192 + sb * 4096;
; #pragma unroll
;             for (int s = 0; s < 2; ++s) {
;                 const s16x4 lo0 = vtr(trs + (16 * s) * VP), hi0 = vtr(trs + (16 * s + 8) * VP);
;                 const s16x4 lo1 = vtr(trs + (16 * s) * VP + 64), hi1 = vtr(trs + (16 * s + 8) * VP + 64);
;                 va[2 * s] = (bf16x8){lo0[0], lo0[1], lo0[2], lo0[3], hi0[0], hi0[1], hi0[2], hi0[3]};
;                 va[2 * s + 1] = (bf16x8){lo1[0], lo1[1], lo1[2], lo1[3], hi1[0], hi1[1], hi1[2], hi1[3]};
;             }
;             if (kb <= 4) {
;                 att_block(kf, qfA, va, oA0, oA1, mA, lA, kb == 0 || kb == 4 || kminA > 32 * kb, mloA - 4 * h - 32 * kb, qc + 128 - 4 * h - 32 * kb);
.LBB0_80:
	v_add_u32_e32 v0, 0xffffffa0, v191
	v_mul_lo_u32 v0, s56, v0
	v_add_u32_e32 v4, s11, v0
	v_max_i32_e32 v164, 0, v4
	v_lshl_add_u64 v[0:1], s[12:13], 0, v[164:165]
	v_lshlrev_b64 v[0:1], 7, v[0:1]
	s_add_i32 s57, s33, 0x1000
	s_lshl_b32 s6, s56, 3
	s_waitcnt vmcnt(0)
	v_lshl_add_u64 v[2:3], v[180:181], 0, v[0:1]
	s_mov_b32 m0, s57
	s_add_i32 s7, s33, 0x3000
	v_add_u32_e32 v4, s6, v4
	global_load_lds_dwordx4 v[2:3], off
	v_lshl_add_u64 v[0:1], v[182:183], 0, v[0:1]
	s_mov_b32 m0, s7
	v_max_i32_e32 v164, 0, v4
	global_load_lds_dwordx4 v[0:1], off
	v_lshl_add_u64 v[0:1], s[12:13], 0, v[164:165]
	v_lshlrev_b64 v[0:1], 7, v[0:1]
	v_readlane_b32 s15, v254, 28
	v_lshl_add_u64 v[2:3], v[180:181], 0, v[0:1]
	s_mov_b32 m0, s15
	v_readlane_b32 s15, v254, 29
	v_add_u32_e32 v4, s6, v4
	global_load_lds_dwordx4 v[2:3], off
	v_lshl_add_u64 v[0:1], v[182:183], 0, v[0:1]
	s_mov_b32 m0, s15
	v_max_i32_e32 v164, 0, v4
	global_load_lds_dwordx4 v[0:1], off
	v_lshl_add_u64 v[0:1], s[12:13], 0, v[164:165]
	v_lshlrev_b64 v[0:1], 7, v[0:1]
	s_add_i32 s15, s33, 0x1800
	v_lshl_add_u64 v[2:3], v[180:181], 0, v[0:1]
	s_mov_b32 m0, s15
	s_add_i32 s17, s33, 0x3800
	v_add_u32_e32 v51, s6, v4
	global_load_lds_dwordx4 v[2:3], off
	v_lshl_add_u64 v[0:1], v[182:183], 0, v[0:1]
	s_mov_b32 m0, s17
	v_max_i32_e32 v164, 0, v51
	global_load_lds_dwordx4 v[0:1], off
	v_lshl_add_u64 v[0:1], s[12:13], 0, v[164:165]
	v_lshlrev_b64 v[0:1], 7, v[0:1]
	s_add_i32 s21, s33, 0x1c00
	v_lshl_add_u64 v[2:3], v[180:181], 0, v[0:1]
	s_mov_b32 m0, s21
	v_readlane_b32 s59, v254, 30
	global_load_lds_dwordx4 v[2:3], off
	v_lshl_add_u64 v[0:1], v[182:183], 0, v[0:1]
	s_mov_b32 m0, s59
	v_max_i32_e32 v199, s58, v189
	global_load_lds_dwordx4 v[0:1], off
	ds_read_b128 v[0:3], v225
	ds_read_b128 v[16:19], v226
	s_waitcnt lgkmcnt(0)
	v_mfma_f32_32x32x16_bf16 v[0:15], v[0:3], v[128:131], 0
	ds_read_b128 v[20:23], v228
	s_mov_b32 s59, 0xff800000
	v_mfma_f32_32x32x16_bf16 v[0:15], v[16:19], v[124:127], v[0:15]
	ds_read_b128 v[16:19], v227
	ds_read_b64_tr_b16 v[34:35], v229 offset:8192
	ds_read_b64_tr_b16 v[36:37], v229 offset:9216
	ds_read_b64_tr_b16 v[40:41], v229 offset:9280
	ds_read_b64_tr_b16 v[38:39], v229 offset:8256
	ds_read_b64_tr_b16 v[42:43], v229 offset:10240
	ds_read_b64_tr_b16 v[44:45], v229 offset:11264
	ds_read_b64_tr_b16 v[48:49], v229 offset:11328
	ds_read_b64_tr_b16 v[46:47], v229 offset:10304
	s_waitcnt lgkmcnt(8)
	v_mfma_f32_32x32x16_bf16 v[0:15], v[16:19], v[120:123], v[0:15]
	v_sub_u32_e32 v16, v199, v193
	v_mov_b32_e32 v17, v214
	s_waitcnt lgkmcnt(0)
	s_nop 0
	v_sub_u32_e32 v18, 0, v16
	v_or_b32_e32 v18, v17, v18
	v_mfma_f32_32x32x16_bf16 v[0:15], v[20:23], v[116:119], v[0:15]
	v_cmp_lt_i32_e32 vcc, -1, v18
	v_sub_u32_e32 v18, 1, v16
	v_add_u32_e32 v19, -1, v17
	v_or_b32_e32 v18, v18, v19
	v_add_u32_e32 v19, -2, v17
	s_nop 6
	v_cndmask_b32_e32 v0, v211, v0, vcc
	v_cmp_lt_i32_e32 vcc, -1, v18
	v_sub_u32_e32 v18, 2, v16
	v_or_b32_e32 v18, v18, v19
	v_cndmask_b32_e32 v1, v211, v1, vcc
	v_cmp_lt_i32_e32 vcc, -1, v18
	v_sub_u32_e32 v18, 3, v16
	v_add_u32_e32 v19, -3, v17
	v_or_b32_e32 v18, v18, v19
	v_cndmask_b32_e32 v2, v211, v2, vcc
	v_cmp_lt_i32_e32 vcc, -1, v18
	v_sub_u32_e32 v18, 8, v16
	v_add_u32_e32 v19, -8, v17
	v_or_b32_e32 v18, v18, v19
	v_cndmask_b32_e32 v3, v211, v3, vcc
	v_cmp_lt_i32_e32 vcc, -1, v18
	v_sub_u32_e32 v18, 9, v16
	v_add_u32_e32 v19, -9, v17
	v_or_b32_e32 v18, v18, v19
	v_cndmask_b32_e32 v4, v211, v4, vcc
	v_cmp_lt_i32_e32 vcc, -1, v18
	v_sub_u32_e32 v18, 10, v16
	v_add_u32_e32 v19, -10, v17
	v_or_b32_e32 v18, v18, v19
	v_cndmask_b32_e32 v5, v211, v5, vcc
	v_cmp_lt_i32_e32 vcc, -1, v18
	v_sub_u32_e32 v18, 11, v16
	v_add_u32_e32 v19, -11, v17
	v_or_b32_e32 v18, v18, v19
	v_cndmask_b32_e32 v6, v211, v6, vcc
	v_cmp_lt_i32_e32 vcc, -1, v18
	v_sub_u32_e32 v18, 16, v16
	v_add_u32_e32 v19, -16, v17
	v_or_b32_e32 v18, v18, v19
	v_cndmask_b32_e32 v7, v211, v7, vcc
	v_cmp_lt_i32_e32 vcc, -1, v18
	v_sub_u32_e32 v18, 17, v16
	v_subrev_u32_e32 v19, 17, v17
	v_or_b32_e32 v18, v18, v19
	v_cndmask_b32_e32 v8, v211, v8, vcc
	v_cmp_lt_i32_e32 vcc, -1, v18
	v_sub_u32_e32 v18, 18, v16
	v_subrev_u32_e32 v19, 18, v17
	v_or_b32_e32 v18, v18, v19
	v_cndmask_b32_e32 v9, v211, v9, vcc
	v_cmp_lt_i32_e32 vcc, -1, v18
	v_sub_u32_e32 v18, 19, v16
	v_subrev_u32_e32 v19, 19, v17
	v_or_b32_e32 v18, v18, v19
	v_cndmask_b32_e32 v10, v211, v10, vcc
	v_cmp_lt_i32_e32 vcc, -1, v18
	v_sub_u32_e32 v18, 24, v16
	v_subrev_u32_e32 v19, 24, v17
	v_or_b32_e32 v18, v18, v19
	v_cndmask_b32_e32 v11, v211, v11, vcc
	v_cmp_lt_i32_e32 vcc, -1, v18
	v_subrev_u32_e32 v18, 25, v17
	s_nop 0
	v_cndmask_b32_e32 v56, v211, v12, vcc
	v_sub_u32_e32 v12, 25, v16
	v_or_b32_e32 v12, v12, v18
	v_cmp_lt_i32_e32 vcc, -1, v12
	v_sub_u32_e32 v12, 26, v16
	s_nop 0
	v_cndmask_b32_e32 v57, v211, v13, vcc
	v_subrev_u32_e32 v13, 26, v17
	v_or_b32_e32 v12, v12, v13
	v_cmp_lt_i32_e32 vcc, -1, v12
	v_sub_u32_e32 v12, 27, v16
	v_subrev_u32_e32 v13, 27, v17
	v_or_b32_e32 v12, v12, v13
	v_cndmask_b32_e32 v58, v211, v14, vcc
	v_cmp_lt_i32_e32 vcc, -1, v12
	v_max3_f32 v12, v0, s59, v1
	v_max3_f32 v12, v12, v2, v3
	v_max3_f32 v12, v12, v4, v5
	v_max3_f32 v12, v12, v6, v7
	v_max3_f32 v12, v12, v8, v9
	v_xor_b32_e32 v13, 32, v206
	v_cndmask_b32_e32 v59, v211, v15, vcc
	v_max3_f32 v12, v12, v10, v11
	v_cmp_lt_i32_e32 vcc, v13, v208
	v_max3_f32 v12, v12, v56, v57
	v_max3_f32 v12, v12, v58, v59
	v_cndmask_b32_e32 v13, v206, v13, vcc
	v_lshlrev_b32_e32 v201, 2, v13
	ds_bpermute_b32 v13, v201, v12
	s_mov_b32 s59, 0xf149f2ca
	s_waitcnt lgkmcnt(0)
; #define LAS __attribute__((address_space(3)))
; __device__ __forceinline__ void att_block(const bf16x8 (&kf)[4], const bf16x8 (&qf)[4], const bf16x8 (&va)[4], f32x16& o0, f32x16& o1, float& mrun, float& lrun, bool domask, int lo_, int hi_) {
;     ...
;     const float mnew = fmaxf(mrun, bmax);
;     float lsum = 0.f;
; #pragma unroll
;     for (int i = 0; i < 16; ++i) { st[i] = __builtin_amdgcn_exp2f(st[i] - mnew); lsum += st[i]; }
;     lsum += __shfl_xor(lsum, 32);
;     const float alpha = __builtin_amdgcn_exp2f(mrun - mnew);
;     lrun = lrun * alpha + lsum; mrun = mnew;
; #pragma unroll
;     for (int i = 0; i < 16; ++i) { o0[i] *= alpha; o1[i] *= alpha; }
; #pragma unroll
;     for (int s = 0; s < 2; ++s) { v4u w; w.x = pk2(st[8 * s], st[8 * s + 1]); w.y = pk2(st[8 * s + 2], st[8 * s + 3]); w.z = pk2(st[8 * s + 4], st[8 * s + 5]); w.w = pk2(st[8 * s + 6], st[8 * s + 7]);
;         const bf16x8 pb = __builtin_bit_cast(bf16x8, w);
;         o0 = __builtin_amdgcn_mfma_f32_32x32x16_bf16(va[2 * s], pb, o0, 0, 0, 0);
;         o1 = __builtin_amdgcn_mfma_f32_32x32x16_bf16(va[2 * s + 1], pb, o1, 0, 0, 0); }
; __device__ __forceinline__ void att_phase(unsigned char* ws, LAS unsigned char* lds, int lane, int wave, int G) {
;     ...
;             asm volatile("s_waitcnt vmcnt(0)" ::: "memory");
;             if (kb < 5) ATT_DMA_KV(P, kb + 1, sb ^ 1);
;             else if (hn) ATT_DMA_KV(N, 0, sb ^ 1);
;             bf16x8 kf[4], va[4];
; #pragma unroll
;             for (int kk = 0; kk < 4; ++kk) kf[kk] = *(LAS const bf16x8*)(kfb + sb * 4096 + (((2 * kk + h) ^ (qc & 7)) << 4));
;             LAS const unsigned char* trs = trb + 8192 + sb * 4096;
; #pragma unroll
;             for (int s = 0; s < 2; ++s) {
;                 const s16x4 lo0 = vtr(trs + (16 * s) * VP), hi0 = vtr(trs + (16 * s + 8) * VP);
;                 const s16x4 lo1 = vtr(trs + (16 * s) * VP + 64), hi1 = vtr(trs + (16 * s + 8) * VP + 64);
;                 va[2 * s] = (bf16x8){lo0[0], lo0[1], lo0[2], lo0[3], hi0[0], hi0[1], hi0[2], hi0[3]};
;                 va[2 * s + 1] = (bf16x8){lo1[0], lo1[1], lo1[2], lo1[3], hi1[0], hi1[1], hi1[2], hi1[3]};
;             }
;             if (kb <= 4) {
;                 att_block(kf, qfA, va, oA0, oA1, mA, lA, kb == 0 || kb == 4 || kminA > 32 * kb, mloA - 4 * h - 32 * kb, qc + 128 - 4 * h - 32 * kb);
	v_max3_f32 v50, v12, v13, s59
	v_sub_f32_e32 v0, v0, v50
	v_exp_f32_e32 v16, v0
	v_sub_f32_e32 v0, v1, v50
	v_exp_f32_e32 v17, v0
	v_sub_f32_e32 v1, v2, v50
	v_exp_f32_e32 v18, v1
	v_sub_f32_e32 v1, v3, v50
	v_exp_f32_e32 v19, v1
	v_sub_f32_e32 v1, v4, v50
	v_add_f32_e32 v0, 0, v16
	v_exp_f32_e32 v20, v1
	v_sub_f32_e32 v1, v5, v50
	v_add_f32_e32 v0, v17, v0
	v_exp_f32_e32 v21, v1
	v_sub_f32_e32 v1, v6, v50
	v_add_f32_e32 v0, v18, v0
	v_exp_f32_e32 v22, v1
	v_sub_f32_e32 v1, v7, v50
	v_add_f32_e32 v0, v19, v0
	v_exp_f32_e32 v23, v1
	v_sub_f32_e32 v1, v8, v50
	v_add_f32_e32 v0, v20, v0
	v_exp_f32_e32 v60, v1
	v_sub_f32_e32 v1, v9, v50
	v_add_f32_e32 v0, v21, v0
	v_exp_f32_e32 v61, v1
	v_add_f32_e32 v0, v22, v0
	v_add_f32_e32 v0, v23, v0
	v_add_f32_e32 v0, v60, v0
	v_add_f32_e32 v62, v61, v0
	v_sub_f32_e32 v0, 0xf149f2ca, v50
	v_exp_f32_e32 v0, v0
	v_sub_f32_e32 v1, v10, v50
	v_cvt_pk_bf16_f32 v52, v16, v17
	v_sub_f32_e32 v16, v56, v50
	v_mul_f32_e32 v0, 0, v0
	v_exp_f32_e32 v63, v1
	v_sub_f32_e32 v64, v11, v50
	v_mov_b32_e32 v1, v0
	v_mov_b32_e32 v2, v0
	v_mov_b32_e32 v3, v0
	v_mov_b32_e32 v4, v0
	v_mov_b32_e32 v5, v0
	v_mov_b32_e32 v6, v0
	v_mov_b32_e32 v7, v0
	v_mov_b32_e32 v8, v0
	v_mov_b32_e32 v9, v0
	v_mov_b32_e32 v10, v0
	v_mov_b32_e32 v11, v0
	v_mov_b32_e32 v12, v0
	v_mov_b32_e32 v13, v0
	v_mov_b32_e32 v14, v0
	v_mov_b32_e32 v15, v0
	v_cvt_pk_bf16_f32 v53, v18, v19
	v_cvt_pk_bf16_f32 v54, v20, v21
	v_cvt_pk_bf16_f32 v55, v22, v23
	v_exp_f32_e32 v56, v16
	v_sub_f32_e32 v16, v57, v50
	v_mfma_f32_32x32x16_bf16 v[18:33], v[34:37], v[52:55], v[0:15]
	v_exp_f32_e32 v57, v16
	v_mov_b64_e32 v[16:17], v[14:15]
	v_sub_f32_e32 v34, v58, v50
	v_exp_f32_e32 v64, v64
	v_cvt_pk_bf16_f32 v36, v56, v57
	s_nop 1
	v_mov_b64_e32 v[14:15], v[12:13]
	v_mov_b64_e32 v[12:13], v[10:11]
	v_mov_b64_e32 v[10:11], v[8:9]
	v_mov_b64_e32 v[8:9], v[6:7]
	v_mov_b64_e32 v[6:7], v[4:5]
	v_mov_b64_e32 v[4:5], v[2:3]
	v_mov_b64_e32 v[2:3], v[0:1]
	v_exp_f32_e32 v1, v34
	v_sub_f32_e32 v34, v59, v50
	v_mfma_f32_32x32x16_bf16 v[2:17], v[38:41], v[52:55], v[2:17]
	v_exp_f32_e32 v38, v34
	v_add_f32_e32 v39, v63, v62
	v_add_f32_e32 v39, v64, v39
	v_cvt_pk_bf16_f32 v34, v60, v61
	v_cvt_pk_bf16_f32 v35, v63, v64
	v_cvt_pk_bf16_f32 v37, v1, v38
	v_add_f32_e32 v39, v56, v39
	v_add_f32_e32 v39, v57, v39
	v_mfma_f32_32x32x16_bf16 v[18:33], v[42:45], v[34:37], v[18:33]
	v_add_f32_e32 v1, v1, v39
	v_add_f32_e32 v1, v38, v1
	ds_bpermute_b32 v232, v201, v1
	v_mfma_f32_32x32x16_bf16 v[2:17], v[46:49], v[34:37], v[2:17]
	v_add_u32_e32 v38, s6, v51
	v_max_i32_e32 v164, 0, v38
	v_lshl_add_u64 v[34:35], s[12:13], 0, v[164:165]
	v_lshlrev_b64 v[34:35], 7, v[34:35]
	s_mov_b32 m0, s33
	s_waitcnt vmcnt(0)
	v_lshl_add_u64 v[36:37], v[180:181], 0, v[34:35]
	v_add_u32_e32 v38, s6, v38
	global_load_lds_dwordx4 v[36:37], off
	v_lshl_add_u64 v[34:35], v[182:183], 0, v[34:35]
	s_mov_b32 m0, s44
	v_max_i32_e32 v164, 0, v38
	global_load_lds_dwordx4 v[34:35], off
	v_lshl_add_u64 v[34:35], s[12:13], 0, v[164:165]
	v_lshlrev_b64 v[34:35], 7, v[34:35]
	v_lshl_add_u64 v[36:37], v[180:181], 0, v[34:35]
	s_mov_b32 m0, s66
	v_add_u32_e32 v38, s6, v38
	global_load_lds_dwordx4 v[36:37], off
	v_lshl_add_u64 v[34:35], v[182:183], 0, v[34:35]
	s_mov_b32 m0, s67
	v_max_i32_e32 v164, 0, v38
	global_load_lds_dwordx4 v[34:35], off
	v_lshl_add_u64 v[34:35], s[12:13], 0, v[164:165]
	v_lshlrev_b64 v[34:35], 7, v[34:35]
	v_lshl_add_u64 v[36:37], v[180:181], 0, v[34:35]
	s_mov_b32 m0, s48
	v_lshl_add_u64 v[34:35], v[182:183], 0, v[34:35]
	global_load_lds_dwordx4 v[36:37], off
	s_mov_b32 m0, s49
	v_readlane_b32 s59, v254, 27
	global_load_lds_dwordx4 v[34:35], off
	v_add_u32_e32 v34, s6, v38
	v_max_i32_e32 v164, 0, v34
	v_lshl_add_u64 v[34:35], s[12:13], 0, v[164:165]
	v_lshlrev_b64 v[34:35], 7, v[34:35]
	v_lshl_add_u64 v[36:37], v[180:181], 0, v[34:35]
	s_mov_b32 m0, s72
	v_lshl_add_u64 v[34:35], v[182:183], 0, v[34:35]
	global_load_lds_dwordx4 v[36:37], off
	s_mov_b32 m0, s59
	s_cmp_gt_i32 s58, 32
	global_load_lds_dwordx4 v[34:35], off
	ds_read_b128 v[68:71], v225 offset:4096
	ds_read_b128 v[64:67], v226 offset:4096
	s_waitcnt lgkmcnt(0)
	v_mfma_f32_32x32x16_bf16 v[34:49], v[68:71], v[128:131], 0
	ds_read_b128 v[60:63], v227 offset:4096
	ds_read_b128 v[56:59], v228 offset:4096
	ds_read_b64_tr_b16 v[52:53], v229 offset:12288
	ds_read_b64_tr_b16 v[54:55], v229 offset:13312
	ds_read_b64_tr_b16 v[94:95], v229 offset:13376
	ds_read_b64_tr_b16 v[92:93], v229 offset:12352
	ds_read_b64_tr_b16 v[88:89], v229 offset:14336
	ds_read_b64_tr_b16 v[90:91], v229 offset:15360
	ds_read_b64_tr_b16 v[86:87], v229 offset:15424
	ds_read_b64_tr_b16 v[84:85], v229 offset:14400
	v_mfma_f32_32x32x16_bf16 v[34:49], v[64:67], v[124:127], v[34:49]
	s_waitcnt lgkmcnt(9)
	v_mfma_f32_32x32x16_bf16 v[34:49], v[60:63], v[120:123], v[34:49]
	s_waitcnt lgkmcnt(8)
	v_mfma_f32_32x32x16_bf16 v[34:49], v[56:59], v[116:119], v[34:49]
	s_cbranch_scc0 .LBB0_82
; __device__ __forceinline__ unsigned pk2(float lo, float hi) { return pg8::cvt_pk_bf16(lo, hi); }
; __device__ __forceinline__ void att_block(const bf16x8 (&kf)[4], const bf16x8 (&qf)[4], const bf16x8 (&va)[4], f32x16& o0, f32x16& o1, float& mrun, float& lrun, bool domask, int lo_, int hi_) {
;     ...
;     if (domask) {
;         asm volatile("" : "+v"(lo_), "+v"(hi_));
; #pragma unroll
;         for (int i = 0; i < 16; ++i) { const int ci = (i & 3) + 8 * (i >> 2); st[i] = ((ci - lo_) | (hi_ - ci)) < 0 ? -INFINITY : st[i]; }
;     }
;     float bmax = -INFINITY;
; #pragma unroll
;     for (int i = 0; i < 16; ++i) bmax = fmaxf(bmax, st[i]);
;     bmax = fmaxf(bmax, __shfl_xor(bmax, 32));
;     const float mnew = fmaxf(mrun, bmax);
;     float lsum = 0.f;
; #pragma unroll
;     for (int i = 0; i < 16; ++i) { st[i] = __builtin_amdgcn_exp2f(st[i] - mnew); lsum += st[i]; }
;     lsum += __shfl_xor(lsum, 32);
;     const float alpha = __builtin_amdgcn_exp2f(mrun - mnew);
;     lrun = lrun * alpha + lsum; mrun = mnew;
; #pragma unroll
;     for (int i = 0; i < 16; ++i) { o0[i] *= alpha; o1[i] *= alpha; }
; #pragma unroll
;     for (int s = 0; s < 2; ++s) { v4u w; w.x = pk2(st[8 * s], st[8 * s + 1]); w.y = pk2(st[8 * s + 2], st[8 * s + 3]); w.z = pk2(st[8 * s + 4], st[8 * s + 5]); w.w = pk2(st[8 * s + 6], st[8 * s + 7]);
;         const bf16x8 pb = __builtin_bit_cast(bf16x8, w);
;         o0 = __builtin_amdgcn_mfma_f32_32x32x16_bf16(va[2 * s], pb, o0, 0, 0, 0);
;         o1 = __builtin_amdgcn_mfma_f32_32x32x16_bf16(va[2 * s + 1], pb, o1, 0, 0, 0); }
	v_sub_u32_e32 v51, v199, v215
	v_mov_b32_e32 v72, v216
	s_nop 0
	v_sub_u32_e32 v73, 0, v51
	v_or_b32_e32 v73, v72, v73
	v_cmp_lt_i32_e32 vcc, -1, v73
	v_sub_u32_e32 v73, 1, v51
	v_add_u32_e32 v74, -1, v72
	v_or_b32_e32 v73, v73, v74
	s_nop 1
	v_cndmask_b32_e32 v34, v211, v34, vcc
	v_cmp_lt_i32_e32 vcc, -1, v73
	v_sub_u32_e32 v73, 2, v51
	v_add_u32_e32 v74, -2, v72
	v_or_b32_e32 v73, v73, v74
	v_cndmask_b32_e32 v35, v211, v35, vcc
	v_cmp_lt_i32_e32 vcc, -1, v73
	v_sub_u32_e32 v73, 3, v51
	v_add_u32_e32 v74, -3, v72
	v_or_b32_e32 v73, v73, v74
	v_cndmask_b32_e32 v36, v211, v36, vcc
	v_cmp_lt_i32_e32 vcc, -1, v73
	v_sub_u32_e32 v73, 8, v51
	v_add_u32_e32 v74, -8, v72
	v_or_b32_e32 v73, v73, v74
	v_cndmask_b32_e32 v37, v211, v37, vcc
	v_cmp_lt_i32_e32 vcc, -1, v73
	v_sub_u32_e32 v73, 9, v51
	v_add_u32_e32 v74, -9, v72
	v_or_b32_e32 v73, v73, v74
	v_cndmask_b32_e32 v38, v211, v38, vcc
	v_cmp_lt_i32_e32 vcc, -1, v73
	v_sub_u32_e32 v73, 10, v51
	v_add_u32_e32 v74, -10, v72
	v_or_b32_e32 v73, v73, v74
	v_cndmask_b32_e32 v39, v211, v39, vcc
	v_cmp_lt_i32_e32 vcc, -1, v73
	v_sub_u32_e32 v73, 11, v51
	v_add_u32_e32 v74, -11, v72
	v_or_b32_e32 v73, v73, v74
	v_cndmask_b32_e32 v40, v211, v40, vcc
	v_cmp_lt_i32_e32 vcc, -1, v73
	v_sub_u32_e32 v73, 16, v51
	v_add_u32_e32 v74, -16, v72
	v_or_b32_e32 v73, v73, v74
	v_cndmask_b32_e32 v41, v211, v41, vcc
	v_cmp_lt_i32_e32 vcc, -1, v73
	v_sub_u32_e32 v73, 17, v51
	v_subrev_u32_e32 v74, 17, v72
	v_or_b32_e32 v73, v73, v74
	v_cndmask_b32_e32 v42, v211, v42, vcc
	v_cmp_lt_i32_e32 vcc, -1, v73
	v_sub_u32_e32 v73, 18, v51
	v_subrev_u32_e32 v74, 18, v72
	v_or_b32_e32 v73, v73, v74
	v_cndmask_b32_e32 v43, v211, v43, vcc
	v_cmp_lt_i32_e32 vcc, -1, v73
	v_sub_u32_e32 v73, 19, v51
	v_subrev_u32_e32 v74, 19, v72
	v_or_b32_e32 v73, v73, v74
	v_cndmask_b32_e32 v44, v211, v44, vcc
	v_cmp_lt_i32_e32 vcc, -1, v73
	v_sub_u32_e32 v73, 24, v51
	v_subrev_u32_e32 v74, 24, v72
	v_or_b32_e32 v73, v73, v74
	v_cndmask_b32_e32 v45, v211, v45, vcc
	v_cmp_lt_i32_e32 vcc, -1, v73
	v_sub_u32_e32 v73, 25, v51
	v_subrev_u32_e32 v74, 25, v72
	v_or_b32_e32 v73, v73, v74
	v_cndmask_b32_e32 v46, v211, v46, vcc
	v_cmp_lt_i32_e32 vcc, -1, v73
	v_sub_u32_e32 v73, 26, v51
	v_subrev_u32_e32 v74, 26, v72
	v_or_b32_e32 v73, v73, v74
	v_sub_u32_e32 v51, 27, v51
	v_subrev_u32_e32 v72, 27, v72
	v_cndmask_b32_e32 v47, v211, v47, vcc
	v_cmp_lt_i32_e32 vcc, -1, v73
	v_or_b32_e32 v51, v51, v72
	s_nop 0
	v_cndmask_b32_e32 v48, v211, v48, vcc
	v_cmp_lt_i32_e32 vcc, -1, v51
	s_nop 1
	v_cndmask_b32_e32 v49, v211, v49, vcc
.LBB0_82:
	s_mov_b32 s59, 0xff800000
	s_nop 9
	v_max3_f32 v51, v34, s59, v35
	v_max3_f32 v51, v51, v36, v37
	v_max3_f32 v51, v51, v38, v39
	v_max3_f32 v51, v51, v40, v41
	v_max3_f32 v51, v51, v42, v43
	v_max3_f32 v51, v51, v44, v45
	v_max3_f32 v51, v51, v46, v47
	v_max3_f32 v51, v51, v48, v49
	ds_bpermute_b32 v72, v201, v51
	v_max_i32_e32 v237, s14, v189
	s_mov_b32 s60, 0xff800000
	s_waitcnt lgkmcnt(0)
	v_max3_f32 v148, v50, v51, v72
	v_sub_f32_e32 v34, v34, v148
	v_exp_f32_e32 v72, v34
	v_sub_f32_e32 v35, v35, v148
	v_exp_f32_e32 v73, v35
	v_sub_f32_e32 v35, v36, v148
	v_exp_f32_e32 v74, v35
	v_sub_f32_e32 v35, v37, v148
	v_exp_f32_e32 v75, v35
	v_sub_f32_e32 v35, v38, v148
	v_add_f32_e32 v34, 0, v72
	v_exp_f32_e32 v76, v35
	v_sub_f32_e32 v35, v39, v148
	v_add_f32_e32 v34, v73, v34
	v_exp_f32_e32 v77, v35
	v_sub_f32_e32 v35, v40, v148
	v_add_f32_e32 v34, v74, v34
	v_exp_f32_e32 v78, v35
	v_sub_f32_e32 v35, v41, v148
	v_add_f32_e32 v34, v75, v34
	v_exp_f32_e32 v79, v35
	v_sub_f32_e32 v35, v42, v148
	v_add_f32_e32 v34, v76, v34
	v_exp_f32_e32 v80, v35
	v_sub_f32_e32 v35, v43, v148
	v_add_f32_e32 v34, v77, v34
	v_exp_f32_e32 v81, v35
	v_sub_f32_e32 v35, v44, v148
	v_add_f32_e32 v34, v78, v34
	v_exp_f32_e32 v82, v35
	v_sub_f32_e32 v35, v45, v148
	v_add_f32_e32 v34, v79, v34
	v_exp_f32_e32 v83, v35
	v_sub_f32_e32 v35, v46, v148
	v_add_f32_e32 v34, v80, v34
	v_exp_f32_e32 v96, v35
	v_sub_f32_e32 v35, v47, v148
	v_add_f32_e32 v34, v81, v34
	v_exp_f32_e32 v97, v35
	v_sub_f32_e32 v35, v48, v148
	v_add_f32_e32 v34, v82, v34
	v_exp_f32_e32 v98, v35
	v_sub_f32_e32 v35, v49, v148
	v_add_f32_e32 v34, v83, v34
	v_exp_f32_e32 v99, v35
	v_add_f32_e32 v34, v96, v34
	v_add_f32_e32 v34, v97, v34
	v_add_f32_e32 v34, v98, v34
	v_add_f32_e32 v235, v99, v34
	v_sub_f32_e32 v34, v50, v148
	v_exp_f32_e32 v188, v34
	ds_bpermute_b32 v236, v201, v235
	v_pk_mul_f32 v[34:35], v[32:33], v[188:189] op_sel_hi:[1,0]
	v_pk_mul_f32 v[32:33], v[30:31], v[188:189] op_sel_hi:[1,0]
	v_pk_mul_f32 v[30:31], v[28:29], v[188:189] op_sel_hi:[1,0]
	v_pk_mul_f32 v[28:29], v[26:27], v[188:189] op_sel_hi:[1,0]
	v_pk_mul_f32 v[26:27], v[24:25], v[188:189] op_sel_hi:[1,0]
	v_pk_mul_f32 v[24:25], v[22:23], v[188:189] op_sel_hi:[1,0]
	v_pk_mul_f32 v[22:23], v[20:21], v[188:189] op_sel_hi:[1,0]
	v_pk_mul_f32 v[20:21], v[18:19], v[188:189] op_sel_hi:[1,0]
	v_pk_mul_f32 v[50:51], v[16:17], v[188:189] op_sel_hi:[1,0]
	v_pk_mul_f32 v[48:49], v[14:15], v[188:189] op_sel_hi:[1,0]
	v_pk_mul_f32 v[46:47], v[12:13], v[188:189] op_sel_hi:[1,0]
	v_pk_mul_f32 v[44:45], v[10:11], v[188:189] op_sel_hi:[1,0]
	v_pk_mul_f32 v[42:43], v[8:9], v[188:189] op_sel_hi:[1,0]
	v_pk_mul_f32 v[40:41], v[6:7], v[188:189] op_sel_hi:[1,0]
	v_pk_mul_f32 v[38:39], v[4:5], v[188:189] op_sel_hi:[1,0]
	v_pk_mul_f32 v[36:37], v[2:3], v[188:189] op_sel_hi:[1,0]
	v_cvt_pk_bf16_f32 v2, v72, v73
	v_cvt_pk_bf16_f32 v3, v74, v75
	v_cvt_pk_bf16_f32 v4, v76, v77
	v_cvt_pk_bf16_f32 v5, v78, v79
	v_sub_u32_e32 v18, v237, v193
	v_mov_b32_e32 v19, v214
	v_mfma_f32_32x32x16_bf16 v[20:35], v[52:55], v[2:5], v[20:35]
	s_waitcnt lgkmcnt(0)
; __device__ __forceinline__ unsigned pk2(float lo, float hi) { return pg8::cvt_pk_bf16(lo, hi); }
; __device__ __forceinline__ void att_block(const bf16x8 (&kf)[4], const bf16x8 (&qf)[4], const bf16x8 (&va)[4], f32x16& o0, f32x16& o1, float& mrun, float& lrun, bool domask, int lo_, int hi_) {
;     f32x16 st;
; #pragma unroll
;     for (int i = 0; i < 16; ++i) st[i] = 0.f;
; #pragma unroll
;     for (int kk = 0; kk < 4; ++kk) st = __builtin_amdgcn_mfma_f32_32x32x16_bf16(kf[kk], qf[kk], st, 0, 0, 0);
;     if (domask) {
;         asm volatile("" : "+v"(lo_), "+v"(hi_));
; #pragma unroll
;         for (int i = 0; i < 16; ++i) { const int ci = (i & 3) + 8 * (i >> 2); st[i] = ((ci - lo_) | (hi_ - ci)) < 0 ? -INFINITY : st[i]; }
;     }
;     float bmax = -INFINITY;
; #pragma unroll
;     for (int i = 0; i < 16; ++i) bmax = fmaxf(bmax, st[i]);
;     bmax = fmaxf(bmax, __shfl_xor(bmax, 32));
;     const float mnew = fmaxf(mrun, bmax);
;     float lsum = 0.f;
; #pragma unroll
;     for (int i = 0; i < 16; ++i) { st[i] = __builtin_amdgcn_exp2f(st[i] - mnew); lsum += st[i]; }
;     lsum += __shfl_xor(lsum, 32);
;     const float alpha = __builtin_amdgcn_exp2f(mrun - mnew);
;     lrun = lrun * alpha + lsum; mrun = mnew;
; #pragma unroll
;     for (int i = 0; i < 16; ++i) { o0[i] *= alpha; o1[i] *= alpha; }
; #pragma unroll
;     for (int s = 0; s < 2; ++s) { v4u w; w.x = pk2(st[8 * s], st[8 * s + 1]); w.y = pk2(st[8 * s + 2], st[8 * s + 3]); w.z = pk2(st[8 * s + 4], st[8 * s + 5]); w.w = pk2(st[8 * s + 6], st[8 * s + 7]);
;         const bf16x8 pb = __builtin_bit_cast(bf16x8, w);
;         o0 = __builtin_amdgcn_mfma_f32_32x32x16_bf16(va[2 * s], pb, o0, 0, 0, 0);
;         o1 = __builtin_amdgcn_mfma_f32_32x32x16_bf16(va[2 * s + 1], pb, o1, 0, 0, 0); }
; __device__ __forceinline__ void att_phase(unsigned char* ws, LAS unsigned char* lds, int lane, int wave, int G) {
;     ...
;             if (kb >= 1) {
;                 att_block(kf, qfB, va, oB0, oB1, mB, lB, kb == 1 || kb == 5 || kminB > 32 * (kb - 1), mloB - 4 * h - 32 * (kb - 1), qc + 128 - 4 * h - 32 * (kb - 1));
	v_mfma_f32_32x32x16_bf16 v[36:51], v[92:95], v[2:5], v[36:51]
	v_cvt_pk_bf16_f32 v2, v80, v81
	v_cvt_pk_bf16_f32 v3, v82, v83
	v_cvt_pk_bf16_f32 v4, v96, v97
	v_cvt_pk_bf16_f32 v5, v98, v99
	s_nop 1
	v_mfma_f32_32x32x16_bf16 v[20:35], v[88:91], v[2:5], v[20:35]
	v_mfma_f32_32x32x16_bf16 v[36:51], v[84:87], v[2:5], v[36:51]
	v_mfma_f32_32x32x16_bf16 v[2:17], v[68:71], v[112:115], 0
	v_mfma_f32_32x32x16_bf16 v[2:17], v[64:67], v[108:111], v[2:17]
	v_mfma_f32_32x32x16_bf16 v[2:17], v[60:63], v[104:107], v[2:17]
	v_mfma_f32_32x32x16_bf16 v[2:17], v[56:59], v[100:103], v[2:17]
	v_sub_u32_e32 v56, 0, v18
	v_or_b32_e32 v56, v19, v56
	v_cmp_lt_i32_e32 vcc, -1, v56
	v_sub_u32_e32 v56, 1, v18
	v_add_u32_e32 v57, -1, v19
	v_or_b32_e32 v56, v56, v57
	v_add_u32_e32 v57, -2, v19
	s_nop 4
	v_cndmask_b32_e32 v2, v211, v2, vcc
	v_cmp_lt_i32_e32 vcc, -1, v56
	v_sub_u32_e32 v56, 2, v18
	v_or_b32_e32 v56, v56, v57
	v_cndmask_b32_e32 v3, v211, v3, vcc
	v_cmp_lt_i32_e32 vcc, -1, v56
	v_sub_u32_e32 v56, 3, v18
	v_add_u32_e32 v57, -3, v19
	v_or_b32_e32 v56, v56, v57
	v_cndmask_b32_e32 v4, v211, v4, vcc
	v_cmp_lt_i32_e32 vcc, -1, v56
	v_sub_u32_e32 v56, 8, v18
	v_add_u32_e32 v57, -8, v19
	v_or_b32_e32 v56, v56, v57
	v_cndmask_b32_e32 v5, v211, v5, vcc
	v_cmp_lt_i32_e32 vcc, -1, v56
	v_sub_u32_e32 v56, 9, v18
	v_add_u32_e32 v57, -9, v19
	v_or_b32_e32 v56, v56, v57
	v_cndmask_b32_e32 v6, v211, v6, vcc
	v_cmp_lt_i32_e32 vcc, -1, v56
	v_sub_u32_e32 v56, 10, v18
	v_add_u32_e32 v57, -10, v19
	v_or_b32_e32 v56, v56, v57
	v_cndmask_b32_e32 v7, v211, v7, vcc
	v_cmp_lt_i32_e32 vcc, -1, v56
	v_sub_u32_e32 v56, 11, v18
	v_add_u32_e32 v57, -11, v19
	v_or_b32_e32 v56, v56, v57
	v_cndmask_b32_e32 v8, v211, v8, vcc
	v_cmp_lt_i32_e32 vcc, -1, v56
	v_sub_u32_e32 v56, 16, v18
	v_add_u32_e32 v57, -16, v19
	v_or_b32_e32 v56, v56, v57
	v_cndmask_b32_e32 v9, v211, v9, vcc
	v_cmp_lt_i32_e32 vcc, -1, v56
	v_sub_u32_e32 v56, 17, v18
	v_subrev_u32_e32 v57, 17, v19
	v_or_b32_e32 v56, v56, v57
	v_cndmask_b32_e32 v10, v211, v10, vcc
	v_cmp_lt_i32_e32 vcc, -1, v56
	v_sub_u32_e32 v56, 18, v18
	v_subrev_u32_e32 v57, 18, v19
	v_or_b32_e32 v56, v56, v57
	v_cndmask_b32_e32 v11, v211, v11, vcc
	v_cmp_lt_i32_e32 vcc, -1, v56
	v_sub_u32_e32 v56, 19, v18
	v_subrev_u32_e32 v57, 19, v19
	v_or_b32_e32 v56, v56, v57
	v_cndmask_b32_e32 v12, v211, v12, vcc
	v_cmp_lt_i32_e32 vcc, -1, v56
	v_sub_u32_e32 v56, 24, v18
	v_subrev_u32_e32 v57, 24, v19
	v_or_b32_e32 v56, v56, v57
	v_cndmask_b32_e32 v13, v211, v13, vcc
	v_cmp_lt_i32_e32 vcc, -1, v56
	v_sub_u32_e32 v56, 25, v18
	v_subrev_u32_e32 v57, 25, v19
	v_or_b32_e32 v56, v56, v57
	v_cndmask_b32_e32 v14, v211, v14, vcc
	v_cmp_lt_i32_e32 vcc, -1, v56
	v_sub_u32_e32 v56, 26, v18
	v_subrev_u32_e32 v57, 26, v19
	v_or_b32_e32 v56, v56, v57
	v_sub_u32_e32 v18, 27, v18
	v_subrev_u32_e32 v19, 27, v19
	v_cndmask_b32_e32 v15, v211, v15, vcc
	v_cmp_lt_i32_e32 vcc, -1, v56
	v_or_b32_e32 v18, v18, v19
	s_nop 0
	v_cndmask_b32_e32 v16, v211, v16, vcc
	v_cmp_lt_i32_e32 vcc, -1, v18
	v_max3_f32 v18, v2, s59, v3
	v_max3_f32 v18, v18, v4, v5
	v_max3_f32 v18, v18, v6, v7
	v_max3_f32 v18, v18, v8, v9
	v_max3_f32 v18, v18, v10, v11
	v_max3_f32 v18, v18, v12, v13
	v_cndmask_b32_e32 v17, v211, v17, vcc
	v_max3_f32 v18, v18, v14, v15
	v_max3_f32 v18, v18, v16, v17
	ds_bpermute_b32 v19, v201, v18
	s_mov_b32 s59, 0xf149f2ca
	s_waitcnt lgkmcnt(0)
	v_max3_f32 v150, v18, v19, s59
	v_sub_f32_e32 v2, v2, v150
	v_exp_f32_e32 v18, v2
	v_sub_f32_e32 v3, v3, v150
	v_exp_f32_e32 v19, v3
	v_sub_f32_e32 v3, v4, v150
	v_exp_f32_e32 v56, v3
	v_sub_f32_e32 v3, v5, v150
	v_exp_f32_e32 v57, v3
	v_sub_f32_e32 v3, v6, v150
	v_add_f32_e32 v2, 0, v18
	v_exp_f32_e32 v58, v3
	v_sub_f32_e32 v3, v7, v150
	v_add_f32_e32 v2, v19, v2
	v_exp_f32_e32 v59, v3
	v_sub_f32_e32 v3, v8, v150
	v_add_f32_e32 v2, v56, v2
	v_exp_f32_e32 v60, v3
	v_sub_f32_e32 v3, v9, v150
	v_add_f32_e32 v2, v57, v2
	v_exp_f32_e32 v61, v3
	v_sub_f32_e32 v3, v10, v150
	v_add_f32_e32 v2, v58, v2
	v_exp_f32_e32 v132, v3
	v_sub_f32_e32 v3, v11, v150
	v_add_f32_e32 v2, v59, v2
	v_exp_f32_e32 v133, v3
	v_sub_f32_e32 v3, v12, v150
	v_add_f32_e32 v2, v60, v2
	v_exp_f32_e32 v134, v3
	v_sub_f32_e32 v3, v13, v150
	v_add_f32_e32 v2, v61, v2
	v_exp_f32_e32 v135, v3
	v_sub_f32_e32 v3, v14, v150
	v_add_f32_e32 v2, v132, v2
	v_exp_f32_e32 v136, v3
	v_sub_f32_e32 v3, v15, v150
	v_add_f32_e32 v2, v133, v2
	v_exp_f32_e32 v137, v3
	v_sub_f32_e32 v3, v16, v150
	v_add_f32_e32 v2, v134, v2
	v_exp_f32_e32 v138, v3
	v_sub_f32_e32 v3, v17, v150
	v_add_f32_e32 v2, v135, v2
	v_exp_f32_e32 v139, v3
	v_add_f32_e32 v2, v136, v2
	v_add_f32_e32 v2, v137, v2
	v_add_f32_e32 v2, v138, v2
	v_add_f32_e32 v233, v139, v2
	v_sub_f32_e32 v2, 0xf149f2ca, v150
	v_exp_f32_e32 v2, v2
	v_cvt_pk_bf16_f32 v96, v18, v19
	v_cvt_pk_bf16_f32 v97, v56, v57
	v_cvt_pk_bf16_f32 v98, v58, v59
	v_mul_f32_e32 v2, 0, v2
	v_mov_b32_e32 v3, v2
	v_mov_b32_e32 v4, v2
	v_mov_b32_e32 v5, v2
	v_mov_b32_e32 v6, v2
	v_mov_b32_e32 v7, v2
	v_mov_b32_e32 v8, v2
	v_mov_b32_e32 v9, v2
	v_mov_b32_e32 v10, v2
	v_mov_b32_e32 v11, v2
	v_mov_b32_e32 v12, v2
	v_mov_b32_e32 v13, v2
	v_mov_b32_e32 v14, v2
	v_mov_b32_e32 v15, v2
	v_mov_b32_e32 v16, v2
	v_mov_b32_e32 v17, v2
	v_cvt_pk_bf16_f32 v99, v60, v61
	ds_bpermute_b32 v234, v201, v233
	s_nop 0
	v_mfma_f32_32x32x16_bf16 v[68:83], v[52:55], v[96:99], v[2:17]
	v_mov_b64_e32 v[66:67], v[16:17]
	v_mov_b64_e32 v[64:65], v[14:15]
	v_mov_b64_e32 v[62:63], v[12:13]
	v_mov_b64_e32 v[60:61], v[10:11]
	v_mov_b64_e32 v[58:59], v[8:9]
	v_mov_b64_e32 v[56:57], v[6:7]
	v_mov_b64_e32 v[54:55], v[4:5]
	v_mov_b64_e32 v[52:53], v[2:3]
	v_cvt_pk_bf16_f32 v4, v132, v133
	v_cvt_pk_bf16_f32 v5, v134, v135
	v_mfma_f32_32x32x16_bf16 v[52:67], v[92:95], v[96:99], v[52:67]
	v_cvt_pk_bf16_f32 v6, v136, v137
	v_cvt_pk_bf16_f32 v7, v138, v139
	s_nop 1
	v_mfma_f32_32x32x16_bf16 v[68:83], v[88:91], v[4:7], v[68:83]
	v_mfma_f32_32x32x16_bf16 v[52:67], v[84:87], v[4:7], v[52:67]
	v_mul_lo_u32 v3, s56, v217
	v_add_u32_e32 v3, s11, v3
	v_max_i32_e32 v164, 0, v3
	v_lshl_add_u64 v[4:5], s[12:13], 0, v[164:165]
	v_lshlrev_b64 v[4:5], 7, v[4:5]
	s_mov_b32 m0, s57
	s_waitcnt vmcnt(0)
; #define LAS __attribute__((address_space(3)))
; __device__ __forceinline__ s16x4 vtr(LAS const unsigned char* p) { return __builtin_bit_cast(s16x4, __builtin_amdgcn_ds_read_tr16_b64_v4i16((LAS v4i16_t*)p)); }
; __device__ __forceinline__ void att_block(const bf16x8 (&kf)[4], const bf16x8 (&qf)[4], const bf16x8 (&va)[4], f32x16& o0, f32x16& o1, float& mrun, float& lrun, bool domask, int lo_, int hi_) {
;     ...
;     if (domask) {
;         asm volatile("" : "+v"(lo_), "+v"(hi_));
; #pragma unroll
;         for (int i = 0; i < 16; ++i) { const int ci = (i & 3) + 8 * (i >> 2); st[i] = ((ci - lo_) | (hi_ - ci)) < 0 ? -INFINITY : st[i]; }
;     }
; __device__ __forceinline__ void att_phase(unsigned char* ws, LAS unsigned char* lds, int lane, int wave, int G) {
;     ...
;             asm volatile("s_waitcnt vmcnt(0)" ::: "memory");
;             if (kb < 5) ATT_DMA_KV(P, kb + 1, sb ^ 1);
;             else if (hn) ATT_DMA_KV(N, 0, sb ^ 1);
;             bf16x8 kf[4], va[4];
; #pragma unroll
;             for (int kk = 0; kk < 4; ++kk) kf[kk] = *(LAS const bf16x8*)(kfb + sb * 4096 + (((2 * kk + h) ^ (qc & 7)) << 4));
;             LAS const unsigned char* trs = trb + 8192 + sb * 4096;
; #pragma unroll
;             for (int s = 0; s < 2; ++s) {
;                 const s16x4 lo0 = vtr(trs + (16 * s) * VP), hi0 = vtr(trs + (16 * s + 8) * VP);
;                 const s16x4 lo1 = vtr(trs + (16 * s) * VP + 64), hi1 = vtr(trs + (16 * s + 8) * VP + 64);
;                 va[2 * s] = (bf16x8){lo0[0], lo0[1], lo0[2], lo0[3], hi0[0], hi0[1], hi0[2], hi0[3]};
;                 va[2 * s + 1] = (bf16x8){lo1[0], lo1[1], lo1[2], lo1[3], hi1[0], hi1[1], hi1[2], hi1[3]};
;             }
;             if (kb <= 4) {
;                 att_block(kf, qfA, va, oA0, oA1, mA, lA, kb == 0 || kb == 4 || kminA > 32 * kb, mloA - 4 * h - 32 * kb, qc + 128 - 4 * h - 32 * kb);
	v_lshl_add_u64 v[6:7], v[180:181], 0, v[4:5]
	v_add_u32_e32 v3, s6, v3
	global_load_lds_dwordx4 v[6:7], off
	v_lshl_add_u64 v[4:5], v[182:183], 0, v[4:5]
	s_mov_b32 m0, s7
	v_max_i32_e32 v164, 0, v3
	global_load_lds_dwordx4 v[4:5], off
	v_lshl_add_u64 v[4:5], s[12:13], 0, v[164:165]
	v_lshlrev_b64 v[4:5], 7, v[4:5]
	v_readlane_b32 s59, v254, 28
	v_lshl_add_u64 v[6:7], v[180:181], 0, v[4:5]
	s_mov_b32 m0, s59
	v_readlane_b32 s59, v254, 29
	v_add_u32_e32 v3, s6, v3
	global_load_lds_dwordx4 v[6:7], off
	v_lshl_add_u64 v[4:5], v[182:183], 0, v[4:5]
	s_mov_b32 m0, s59
	v_max_i32_e32 v164, 0, v3
	global_load_lds_dwordx4 v[4:5], off
	v_lshl_add_u64 v[4:5], s[12:13], 0, v[164:165]
	v_lshlrev_b64 v[4:5], 7, v[4:5]
	v_lshl_add_u64 v[6:7], v[180:181], 0, v[4:5]
	s_mov_b32 m0, s15
	v_add_u32_e32 v3, s6, v3
	global_load_lds_dwordx4 v[6:7], off
	v_lshl_add_u64 v[4:5], v[182:183], 0, v[4:5]
	s_mov_b32 m0, s17
	v_max_i32_e32 v164, 0, v3
	global_load_lds_dwordx4 v[4:5], off
	v_lshl_add_u64 v[4:5], s[12:13], 0, v[164:165]
	v_lshlrev_b64 v[4:5], 7, v[4:5]
	v_lshl_add_u64 v[6:7], v[180:181], 0, v[4:5]
	s_mov_b32 m0, s21
	v_readlane_b32 s59, v254, 30
	global_load_lds_dwordx4 v[6:7], off
	v_lshl_add_u64 v[4:5], v[182:183], 0, v[4:5]
	s_mov_b32 m0, s59
	s_cmpk_lt_i32 s58, 0x41
	global_load_lds_dwordx4 v[4:5], off
	ds_read_b128 v[144:147], v225
	ds_read_b128 v[140:143], v226
	s_waitcnt lgkmcnt(0)
	v_mfma_f32_32x32x16_bf16 v[4:19], v[144:147], v[128:131], 0
	ds_read_b128 v[136:139], v227
	ds_read_b128 v[132:135], v228
	ds_read_b64_tr_b16 v[96:97], v229 offset:8192
	ds_read_b64_tr_b16 v[98:99], v229 offset:9216
	ds_read_b64_tr_b16 v[94:95], v229 offset:9280
	ds_read_b64_tr_b16 v[92:93], v229 offset:8256
	ds_read_b64_tr_b16 v[88:89], v229 offset:10240
	ds_read_b64_tr_b16 v[90:91], v229 offset:11264
	ds_read_b64_tr_b16 v[86:87], v229 offset:11328
	ds_read_b64_tr_b16 v[84:85], v229 offset:10304
	v_mfma_f32_32x32x16_bf16 v[4:19], v[140:143], v[124:127], v[4:19]
	s_waitcnt lgkmcnt(9)
	v_mfma_f32_32x32x16_bf16 v[4:19], v[136:139], v[120:123], v[4:19]
	s_waitcnt lgkmcnt(8)
	v_mfma_f32_32x32x16_bf16 v[4:19], v[132:135], v[116:119], v[4:19]
	s_cbranch_scc1 .LBB0_84
	v_sub_u32_e32 v3, v199, v218
	v_mov_b32_e32 v149, v219
	s_nop 0
	v_sub_u32_e32 v151, 0, v3
	v_or_b32_e32 v151, v149, v151
	v_cmp_lt_i32_e32 vcc, -1, v151
	v_sub_u32_e32 v151, 1, v3
	v_add_u32_e32 v152, -1, v149
	v_or_b32_e32 v151, v151, v152
	s_nop 1
	v_cndmask_b32_e32 v4, v211, v4, vcc
	v_cmp_lt_i32_e32 vcc, -1, v151
	v_sub_u32_e32 v151, 2, v3
	v_add_u32_e32 v152, -2, v149
	v_or_b32_e32 v151, v151, v152
	v_cndmask_b32_e32 v5, v211, v5, vcc
	v_cmp_lt_i32_e32 vcc, -1, v151
	v_sub_u32_e32 v151, 3, v3
	v_add_u32_e32 v152, -3, v149
	v_or_b32_e32 v151, v151, v152
	v_cndmask_b32_e32 v6, v211, v6, vcc
	v_cmp_lt_i32_e32 vcc, -1, v151
	v_sub_u32_e32 v151, 8, v3
	v_add_u32_e32 v152, -8, v149
	v_or_b32_e32 v151, v151, v152
	v_cndmask_b32_e32 v7, v211, v7, vcc
	v_cmp_lt_i32_e32 vcc, -1, v151
	v_sub_u32_e32 v151, 9, v3
	v_add_u32_e32 v152, -9, v149
	v_or_b32_e32 v151, v151, v152
	v_cndmask_b32_e32 v8, v211, v8, vcc
	v_cmp_lt_i32_e32 vcc, -1, v151
	v_sub_u32_e32 v151, 10, v3
	v_add_u32_e32 v152, -10, v149
	v_or_b32_e32 v151, v151, v152
	v_cndmask_b32_e32 v9, v211, v9, vcc
	v_cmp_lt_i32_e32 vcc, -1, v151
	v_sub_u32_e32 v151, 11, v3
	v_add_u32_e32 v152, -11, v149
	v_or_b32_e32 v151, v151, v152
	v_cndmask_b32_e32 v10, v211, v10, vcc
	v_cmp_lt_i32_e32 vcc, -1, v151
	v_sub_u32_e32 v151, 16, v3
	v_add_u32_e32 v152, -16, v149
	v_or_b32_e32 v151, v151, v152
	v_cndmask_b32_e32 v11, v211, v11, vcc
	v_cmp_lt_i32_e32 vcc, -1, v151
	v_sub_u32_e32 v151, 17, v3
	v_subrev_u32_e32 v152, 17, v149
	v_or_b32_e32 v151, v151, v152
	v_cndmask_b32_e32 v12, v211, v12, vcc
	v_cmp_lt_i32_e32 vcc, -1, v151
	v_sub_u32_e32 v151, 18, v3
	v_subrev_u32_e32 v152, 18, v149
	v_or_b32_e32 v151, v151, v152
	v_cndmask_b32_e32 v13, v211, v13, vcc
	v_cmp_lt_i32_e32 vcc, -1, v151
	v_sub_u32_e32 v151, 19, v3
	v_subrev_u32_e32 v152, 19, v149
	v_or_b32_e32 v151, v151, v152
	v_cndmask_b32_e32 v14, v211, v14, vcc
	v_cmp_lt_i32_e32 vcc, -1, v151
	v_sub_u32_e32 v151, 24, v3
	v_subrev_u32_e32 v152, 24, v149
	v_or_b32_e32 v151, v151, v152
	v_cndmask_b32_e32 v15, v211, v15, vcc
	v_cmp_lt_i32_e32 vcc, -1, v151
	v_sub_u32_e32 v151, 25, v3
	v_subrev_u32_e32 v152, 25, v149
	v_or_b32_e32 v151, v151, v152
	v_cndmask_b32_e32 v16, v211, v16, vcc
	v_cmp_lt_i32_e32 vcc, -1, v151
	v_sub_u32_e32 v151, 26, v3
	v_subrev_u32_e32 v152, 26, v149
	v_or_b32_e32 v151, v151, v152
	v_sub_u32_e32 v3, 27, v3
	v_subrev_u32_e32 v149, 27, v149
	v_cndmask_b32_e32 v17, v211, v17, vcc
	v_cmp_lt_i32_e32 vcc, -1, v151
	v_or_b32_e32 v3, v3, v149
	s_nop 0
	v_cndmask_b32_e32 v18, v211, v18, vcc
	v_cmp_lt_i32_e32 vcc, -1, v3
	s_nop 1
	v_cndmask_b32_e32 v19, v211, v19, vcc

; #define LAS __attribute__((address_space(3)))
; __device__ __forceinline__ void att_block(const bf16x8 (&kf)[4], const bf16x8 (&qf)[4], const bf16x8 (&va)[4], f32x16& o0, f32x16& o1, float& mrun, float& lrun, bool domask, int lo_, int hi_) {
;     f32x16 st;
; #pragma unroll
;     for (int i = 0; i < 16; ++i) st[i] = 0.f;
; #pragma unroll
;     for (int kk = 0; kk < 4; ++kk) st = __builtin_amdgcn_mfma_f32_32x32x16_bf16(kf[kk], qf[kk], st, 0, 0, 0);
;     if (domask) {
;         asm volatile("" : "+v"(lo_), "+v"(hi_));
; #pragma unroll
;         for (int i = 0; i < 16; ++i) { const int ci = (i & 3) + 8 * (i >> 2); st[i] = ((ci - lo_) | (hi_ - ci)) < 0 ? -INFINITY : st[i]; }
;     }
;     float bmax = -INFINITY;
; #pragma unroll
;     for (int i = 0; i < 16; ++i) bmax = fmaxf(bmax, st[i]);
;     bmax = fmaxf(bmax, __shfl_xor(bmax, 32));
;     const float mnew = fmaxf(mrun, bmax);
;     float lsum = 0.f;
; #pragma unroll
;     for (int i = 0; i < 16; ++i) { st[i] = __builtin_amdgcn_exp2f(st[i] - mnew); lsum += st[i]; }
;     lsum += __shfl_xor(lsum, 32);
;     const float alpha = __builtin_amdgcn_exp2f(mrun - mnew);
;     lrun = lrun * alpha + lsum; mrun = mnew;
; #pragma unroll
;     for (int i = 0; i < 16; ++i) { o0[i] *= alpha; o1[i] *= alpha; }
; #pragma unroll
;     for (int s = 0; s < 2; ++s) { v4u w; w.x = pk2(st[8 * s], st[8 * s + 1]); w.y = pk2(st[8 * s + 2], st[8 * s + 3]); w.z = pk2(st[8 * s + 4], st[8 * s + 5]); w.w = pk2(st[8 * s + 6], st[8 * s + 7]);
;         const bf16x8 pb = __builtin_bit_cast(bf16x8, w);
;         o0 = __builtin_amdgcn_mfma_f32_32x32x16_bf16(va[2 * s], pb, o0, 0, 0, 0);
;         o1 = __builtin_amdgcn_mfma_f32_32x32x16_bf16(va[2 * s + 1], pb, o1, 0, 0, 0); }
; __device__ __forceinline__ void att_phase(unsigned char* ws, LAS unsigned char* lds, int lane, int wave, int G) {
;     ...
;         for (int kb = 0; kb < 6; ++kb) {
;             asm volatile("s_waitcnt vmcnt(0)" ::: "memory");
;             if (kb < 5) ATT_DMA_KV(P, kb + 1, sb ^ 1);
;             else if (hn) ATT_DMA_KV(N, 0, sb ^ 1);
;             bf16x8 kf[4], va[4];
; #pragma unroll
;             for (int kk = 0; kk < 4; ++kk) kf[kk] = *(LAS const bf16x8*)(kfb + sb * 4096 + (((2 * kk + h) ^ (qc & 7)) << 4));
;             LAS const unsigned char* trs = trb + 8192 + sb * 4096;
; #pragma unroll
;             for (int s = 0; s < 2; ++s) {
.LBB0_86:
	s_nop 10
	v_max3_f32 v3, v36, s60, v37
	v_max3_f32 v3, v3, v38, v39
	v_max3_f32 v3, v3, v40, v41
	v_max3_f32 v3, v3, v42, v43
	v_max3_f32 v3, v3, v44, v45
	v_max3_f32 v3, v3, v46, v47
	v_max3_f32 v3, v3, v48, v49
	v_max3_f32 v3, v3, v50, v51
	ds_bpermute_b32 v132, v201, v3
	s_waitcnt lgkmcnt(0)
	s_waitcnt lgkmcnt(0)
	v_max3_f32 v148, v150, v3, v132
	v_sub_f32_e32 v3, v36, v148
	v_sub_f32_e32 v36, v37, v148
	v_exp_f32_e32 v133, v36
	v_sub_f32_e32 v36, v38, v148
	v_exp_f32_e32 v134, v36
	v_sub_f32_e32 v36, v39, v148
	v_exp_f32_e32 v135, v36
	v_sub_f32_e32 v36, v40, v148
	v_exp_f32_e32 v136, v36
	v_sub_f32_e32 v36, v41, v148
	v_exp_f32_e32 v137, v36
	v_sub_f32_e32 v36, v42, v148
	v_exp_f32_e32 v138, v36
	v_sub_f32_e32 v36, v43, v148
	v_exp_f32_e32 v139, v36
	v_sub_f32_e32 v36, v44, v148
	v_exp_f32_e32 v140, v36
	v_sub_f32_e32 v36, v45, v148
	v_exp_f32_e32 v141, v36
	v_sub_f32_e32 v36, v46, v148
	v_exp_f32_e32 v142, v36
	v_sub_f32_e32 v36, v47, v148
	v_exp_f32_e32 v143, v36
	v_sub_f32_e32 v36, v48, v148
	v_exp_f32_e32 v132, v3
	v_exp_f32_e32 v144, v36
	v_sub_f32_e32 v36, v49, v148
	v_exp_f32_e32 v145, v36
	v_sub_f32_e32 v36, v50, v148
	v_exp_f32_e32 v146, v36
	v_sub_f32_e32 v36, v51, v148
	v_exp_f32_e32 v147, v36
	v_sub_f32_e32 v36, v150, v148
	v_add_f32_e32 v3, 0, v132
	v_exp_f32_e32 v190, v36
	v_add_f32_e32 v3, v133, v3
	v_add_f32_e32 v3, v134, v3
	v_add_f32_e32 v3, v135, v3
	v_add_f32_e32 v3, v136, v3
	v_pk_mul_f32 v[50:51], v[82:83], v[190:191] op_sel_hi:[1,0]
	v_pk_mul_f32 v[48:49], v[80:81], v[190:191] op_sel_hi:[1,0]
	v_pk_mul_f32 v[46:47], v[78:79], v[190:191] op_sel_hi:[1,0]
	v_pk_mul_f32 v[44:45], v[76:77], v[190:191] op_sel_hi:[1,0]
	v_pk_mul_f32 v[42:43], v[74:75], v[190:191] op_sel_hi:[1,0]
	v_pk_mul_f32 v[40:41], v[72:73], v[190:191] op_sel_hi:[1,0]
	v_pk_mul_f32 v[38:39], v[70:71], v[190:191] op_sel_hi:[1,0]
	v_pk_mul_f32 v[36:37], v[68:69], v[190:191] op_sel_hi:[1,0]
	v_pk_mul_f32 v[66:67], v[66:67], v[190:191] op_sel_hi:[1,0]
	v_pk_mul_f32 v[64:65], v[64:65], v[190:191] op_sel_hi:[1,0]
	v_pk_mul_f32 v[62:63], v[62:63], v[190:191] op_sel_hi:[1,0]
	v_pk_mul_f32 v[60:61], v[60:61], v[190:191] op_sel_hi:[1,0]
	v_pk_mul_f32 v[58:59], v[58:59], v[190:191] op_sel_hi:[1,0]
	v_pk_mul_f32 v[56:57], v[56:57], v[190:191] op_sel_hi:[1,0]
	v_pk_mul_f32 v[54:55], v[54:55], v[190:191] op_sel_hi:[1,0]
	v_pk_mul_f32 v[52:53], v[52:53], v[190:191] op_sel_hi:[1,0]
	v_cvt_pk_bf16_f32 v68, v132, v133
	v_cvt_pk_bf16_f32 v69, v134, v135
	v_cvt_pk_bf16_f32 v70, v136, v137
	v_cvt_pk_bf16_f32 v71, v138, v139
	v_add_f32_e32 v3, v137, v3
	v_add_f32_e32 v3, v138, v3
	v_mfma_f32_32x32x16_bf16 v[36:51], v[96:99], v[68:71], v[36:51]
	v_add_f32_e32 v3, v139, v3
	v_add_f32_e32 v3, v140, v3
	v_add_f32_e32 v3, v141, v3
	v_add_f32_e32 v3, v142, v3
	v_add_f32_e32 v3, v143, v3
	v_add_f32_e32 v3, v144, v3
	v_add_f32_e32 v3, v145, v3
	v_mfma_f32_32x32x16_bf16 v[52:67], v[92:95], v[68:71], v[52:67]
	v_cvt_pk_bf16_f32 v68, v140, v141
	v_cvt_pk_bf16_f32 v69, v142, v143
	v_cvt_pk_bf16_f32 v70, v144, v145
	v_cvt_pk_bf16_f32 v71, v146, v147
	v_add_f32_e32 v3, v146, v3
	v_add_f32_e32 v3, v147, v3
	ds_bpermute_b32 v238, v201, v3
	v_mfma_f32_32x32x16_bf16 v[36:51], v[88:91], v[68:71], v[36:51]
	v_mfma_f32_32x32x16_bf16 v[52:67], v[84:87], v[68:71], v[52:67]
	v_mul_lo_u32 v68, s56, v191
	v_add_u32_e32 v72, s11, v68
	v_max_i32_e32 v164, 0, v72
	v_lshl_add_u64 v[68:69], s[12:13], 0, v[164:165]
	v_lshlrev_b64 v[68:69], 7, v[68:69]
	s_mov_b32 m0, s33
	s_waitcnt vmcnt(0)
	v_lshl_add_u64 v[70:71], v[180:181], 0, v[68:69]
	v_add_u32_e32 v72, s6, v72
	global_load_lds_dwordx4 v[70:71], off
	v_lshl_add_u64 v[68:69], v[182:183], 0, v[68:69]
	s_mov_b32 m0, s44
	v_max_i32_e32 v164, 0, v72
	global_load_lds_dwordx4 v[68:69], off
	v_lshl_add_u64 v[68:69], s[12:13], 0, v[164:165]
	v_lshlrev_b64 v[68:69], 7, v[68:69]
	v_lshl_add_u64 v[70:71], v[180:181], 0, v[68:69]
	s_mov_b32 m0, s66
	v_add_u32_e32 v72, s6, v72
	global_load_lds_dwordx4 v[70:71], off
	v_lshl_add_u64 v[68:69], v[182:183], 0, v[68:69]
	s_mov_b32 m0, s67
	v_max_i32_e32 v164, 0, v72
	global_load_lds_dwordx4 v[68:69], off
	v_lshl_add_u64 v[68:69], s[12:13], 0, v[164:165]
	v_lshlrev_b64 v[68:69], 7, v[68:69]
	v_lshl_add_u64 v[70:71], v[180:181], 0, v[68:69]
	s_mov_b32 m0, s48
	v_lshl_add_u64 v[68:69], v[182:183], 0, v[68:69]
	global_load_lds_dwordx4 v[70:71], off
	s_mov_b32 m0, s49
	v_readlane_b32 s59, v254, 27
	global_load_lds_dwordx4 v[68:69], off
	v_add_u32_e32 v68, s6, v72
	v_max_i32_e32 v164, 0, v68
	v_lshl_add_u64 v[68:69], s[12:13], 0, v[164:165]
	v_lshlrev_b64 v[68:69], 7, v[68:69]
	v_lshl_add_u64 v[70:71], v[180:181], 0, v[68:69]
	s_mov_b32 m0, s72
	v_lshl_add_u64 v[68:69], v[182:183], 0, v[68:69]
	global_load_lds_dwordx4 v[70:71], off
	s_mov_b32 m0, s59
	s_cmpk_lt_i32 s58, 0x61
	global_load_lds_dwordx4 v[68:69], off
	ds_read_b128 v[96:99], v225 offset:4096
	ds_read_b128 v[92:95], v226 offset:4096
	s_waitcnt lgkmcnt(0)
	v_mfma_f32_32x32x16_bf16 v[68:83], v[96:99], v[128:131], 0
	ds_read_b128 v[88:91], v227 offset:4096
	ds_read_b128 v[84:87], v228 offset:4096
	ds_read_b64_tr_b16 v[144:145], v229 offset:12288
	ds_read_b64_tr_b16 v[146:147], v229 offset:13312
	ds_read_b64_tr_b16 v[142:143], v229 offset:13376
	ds_read_b64_tr_b16 v[140:141], v229 offset:12352
	ds_read_b64_tr_b16 v[136:137], v229 offset:14336
	ds_read_b64_tr_b16 v[138:139], v229 offset:15360
	ds_read_b64_tr_b16 v[134:135], v229 offset:15424
	ds_read_b64_tr_b16 v[132:133], v229 offset:14400
	v_mfma_f32_32x32x16_bf16 v[68:83], v[92:95], v[124:127], v[68:83]
	s_waitcnt lgkmcnt(9)
	v_mfma_f32_32x32x16_bf16 v[68:83], v[88:91], v[120:123], v[68:83]
	s_waitcnt lgkmcnt(8)
	v_mfma_f32_32x32x16_bf16 v[68:83], v[84:87], v[116:119], v[68:83]
	s_cbranch_scc1 .LBB0_88
; __device__ __forceinline__ void att_block(const bf16x8 (&kf)[4], const bf16x8 (&qf)[4], const bf16x8 (&va)[4], f32x16& o0, f32x16& o1, float& mrun, float& lrun, bool domask, int lo_, int hi_) {
;     ...
;     if (domask) {
;         asm volatile("" : "+v"(lo_), "+v"(hi_));
; #pragma unroll
;         for (int i = 0; i < 16; ++i) { const int ci = (i & 3) + 8 * (i >> 2); st[i] = ((ci - lo_) | (hi_ - ci)) < 0 ? -INFINITY : st[i]; }
;     }
	v_sub_u32_e32 v150, v199, v220
	v_mov_b32_e32 v151, v221
	s_nop 0
	v_sub_u32_e32 v152, 0, v150
	v_or_b32_e32 v152, v151, v152
	v_cmp_lt_i32_e32 vcc, -1, v152
	v_sub_u32_e32 v152, 1, v150
	v_add_u32_e32 v153, -1, v151
	v_or_b32_e32 v152, v152, v153
	s_nop 1
	v_cndmask_b32_e32 v68, v211, v68, vcc
	v_cmp_lt_i32_e32 vcc, -1, v152
	v_sub_u32_e32 v152, 2, v150
	v_add_u32_e32 v153, -2, v151
	v_or_b32_e32 v152, v152, v153
	v_cndmask_b32_e32 v69, v211, v69, vcc
	v_cmp_lt_i32_e32 vcc, -1, v152
	v_sub_u32_e32 v152, 3, v150
	v_add_u32_e32 v153, -3, v151
	v_or_b32_e32 v152, v152, v153
	v_cndmask_b32_e32 v70, v211, v70, vcc
	v_cmp_lt_i32_e32 vcc, -1, v152
	v_sub_u32_e32 v152, 8, v150
	v_add_u32_e32 v153, -8, v151
	v_or_b32_e32 v152, v152, v153
	v_cndmask_b32_e32 v71, v211, v71, vcc
	v_cmp_lt_i32_e32 vcc, -1, v152
	v_sub_u32_e32 v152, 9, v150
	v_add_u32_e32 v153, -9, v151
	v_or_b32_e32 v152, v152, v153
	v_cndmask_b32_e32 v72, v211, v72, vcc
	v_cmp_lt_i32_e32 vcc, -1, v152
	v_sub_u32_e32 v152, 10, v150
	v_add_u32_e32 v153, -10, v151
	v_or_b32_e32 v152, v152, v153
	v_cndmask_b32_e32 v73, v211, v73, vcc
	v_cmp_lt_i32_e32 vcc, -1, v152
	v_sub_u32_e32 v152, 11, v150
	v_add_u32_e32 v153, -11, v151
	v_or_b32_e32 v152, v152, v153
	v_cndmask_b32_e32 v74, v211, v74, vcc
	v_cmp_lt_i32_e32 vcc, -1, v152
	v_sub_u32_e32 v152, 16, v150
	v_add_u32_e32 v153, -16, v151
	v_or_b32_e32 v152, v152, v153
	v_cndmask_b32_e32 v75, v211, v75, vcc
	v_cmp_lt_i32_e32 vcc, -1, v152
	v_sub_u32_e32 v152, 17, v150
	v_subrev_u32_e32 v153, 17, v151
	v_or_b32_e32 v152, v152, v153
	v_cndmask_b32_e32 v76, v211, v76, vcc
	v_cmp_lt_i32_e32 vcc, -1, v152
	v_sub_u32_e32 v152, 18, v150
	v_subrev_u32_e32 v153, 18, v151
	v_or_b32_e32 v152, v152, v153
	v_cndmask_b32_e32 v77, v211, v77, vcc
	v_cmp_lt_i32_e32 vcc, -1, v152
	v_sub_u32_e32 v152, 19, v150
	v_subrev_u32_e32 v153, 19, v151
	v_or_b32_e32 v152, v152, v153
	v_cndmask_b32_e32 v78, v211, v78, vcc
	v_cmp_lt_i32_e32 vcc, -1, v152
	v_sub_u32_e32 v152, 24, v150
	v_subrev_u32_e32 v153, 24, v151
	v_or_b32_e32 v152, v152, v153
	v_cndmask_b32_e32 v79, v211, v79, vcc
	v_cmp_lt_i32_e32 vcc, -1, v152
	v_sub_u32_e32 v152, 25, v150
	v_subrev_u32_e32 v153, 25, v151
	v_or_b32_e32 v152, v152, v153
	v_cndmask_b32_e32 v80, v211, v80, vcc
	v_cmp_lt_i32_e32 vcc, -1, v152
	v_sub_u32_e32 v152, 26, v150
	v_subrev_u32_e32 v153, 26, v151
	v_or_b32_e32 v152, v152, v153
	v_sub_u32_e32 v150, 27, v150
	v_subrev_u32_e32 v151, 27, v151
	v_cndmask_b32_e32 v81, v211, v81, vcc
	v_cmp_lt_i32_e32 vcc, -1, v152
	v_or_b32_e32 v150, v150, v151
	s_nop 0
	v_cndmask_b32_e32 v82, v211, v82, vcc
	v_cmp_lt_i32_e32 vcc, -1, v150
	s_nop 1
	v_cndmask_b32_e32 v83, v211, v83, vcc

; #define LAS __attribute__((address_space(3)))
; __device__ __forceinline__ void att_block(const bf16x8 (&kf)[4], const bf16x8 (&qf)[4], const bf16x8 (&va)[4], f32x16& o0, f32x16& o1, float& mrun, float& lrun, bool domask, int lo_, int hi_) {
;     ...
;     float bmax = -INFINITY;
; #pragma unroll
;     for (int i = 0; i < 16; ++i) bmax = fmaxf(bmax, st[i]);
;     bmax = fmaxf(bmax, __shfl_xor(bmax, 32));
;     const float mnew = fmaxf(mrun, bmax);
;     float lsum = 0.f;
; #pragma unroll
;     for (int i = 0; i < 16; ++i) { st[i] = __builtin_amdgcn_exp2f(st[i] - mnew); lsum += st[i]; }
;     lsum += __shfl_xor(lsum, 32);
;     const float alpha = __builtin_amdgcn_exp2f(mrun - mnew);
;     lrun = lrun * alpha + lsum; mrun = mnew;
; #pragma unroll
;     for (int i = 0; i < 16; ++i) { o0[i] *= alpha; o1[i] *= alpha; }
; #pragma unroll
;     for (int s = 0; s < 2; ++s) { v4u w; w.x = pk2(st[8 * s], st[8 * s + 1]); w.y = pk2(st[8 * s + 2], st[8 * s + 3]); w.z = pk2(st[8 * s + 4], st[8 * s + 5]); w.w = pk2(st[8 * s + 6], st[8 * s + 7]);
;         const bf16x8 pb = __builtin_bit_cast(bf16x8, w);
;         o0 = __builtin_amdgcn_mfma_f32_32x32x16_bf16(va[2 * s], pb, o0, 0, 0, 0);
;         o1 = __builtin_amdgcn_mfma_f32_32x32x16_bf16(va[2 * s + 1], pb, o1, 0, 0, 0); }
; __device__ __forceinline__ void att_phase(unsigned char* ws, LAS unsigned char* lds, int lane, int wave, int G) {
;     ...
;             asm volatile("s_waitcnt vmcnt(0)" ::: "memory");
;             if (kb < 5) ATT_DMA_KV(P, kb + 1, sb ^ 1);
;             else if (hn) ATT_DMA_KV(N, 0, sb ^ 1);
;             bf16x8 kf[4], va[4];
; #pragma unroll
;             for (int kk = 0; kk < 4; ++kk) kf[kk] = *(LAS const bf16x8*)(kfb + sb * 4096 + (((2 * kk + h) ^ (qc & 7)) << 4));
;             LAS const unsigned char* trs = trb + 8192 + sb * 4096;
; #pragma unroll
;             for (int s = 0; s < 2; ++s) {
;                 const s16x4 lo0 = vtr(trs + (16 * s) * VP), hi0 = vtr(trs + (16 * s + 8) * VP);
;                 const s16x4 lo1 = vtr(trs + (16 * s) * VP + 64), hi1 = vtr(trs + (16 * s + 8) * VP + 64);
;                 va[2 * s] = (bf16x8){lo0[0], lo0[1], lo0[2], lo0[3], hi0[0], hi0[1], hi0[2], hi0[3]};
;                 va[2 * s + 1] = (bf16x8){lo1[0], lo1[1], lo1[2], lo1[3], hi1[0], hi1[1], hi1[2], hi1[3]};
;             }
.LBB0_90:
	v_mul_lo_u32 v84, s52, v189
	s_mov_b32 s58, 0xff800000
	v_add_u32_e32 v198, s53, v84
	s_nop 7
	v_max3_f32 v84, v68, s58, v69
	v_max3_f32 v84, v84, v70, v71
	v_max3_f32 v84, v84, v72, v73
	v_max3_f32 v84, v84, v74, v75
	v_max3_f32 v84, v84, v76, v77
	v_max3_f32 v84, v84, v78, v79
	v_max3_f32 v84, v84, v80, v81
	v_max3_f32 v84, v84, v82, v83
	ds_bpermute_b32 v85, v201, v84
	s_waitcnt lgkmcnt(0)
	s_waitcnt lgkmcnt(0)
	v_max3_f32 v245, v148, v84, v85
	v_sub_f32_e32 v68, v68, v245
	v_exp_f32_e32 v149, v68
	v_sub_f32_e32 v69, v69, v245
	v_exp_f32_e32 v150, v69
	v_sub_f32_e32 v69, v70, v245
	v_exp_f32_e32 v151, v69
	v_sub_f32_e32 v69, v71, v245
	v_exp_f32_e32 v152, v69
	v_sub_f32_e32 v69, v72, v245
	v_add_f32_e32 v68, 0, v149
	v_exp_f32_e32 v153, v69
	v_sub_f32_e32 v69, v73, v245
	v_add_f32_e32 v68, v150, v68
	v_exp_f32_e32 v154, v69
	v_sub_f32_e32 v69, v74, v245
	v_add_f32_e32 v68, v151, v68
	v_exp_f32_e32 v155, v69
	v_sub_f32_e32 v69, v75, v245
	v_add_f32_e32 v68, v152, v68
	v_exp_f32_e32 v156, v69
	v_sub_f32_e32 v69, v76, v245
	v_add_f32_e32 v68, v153, v68
	v_exp_f32_e32 v157, v69
	v_sub_f32_e32 v69, v77, v245
	v_add_f32_e32 v68, v154, v68
	v_exp_f32_e32 v158, v69
	v_sub_f32_e32 v69, v78, v245
	v_add_f32_e32 v68, v155, v68
	v_exp_f32_e32 v159, v69
	v_sub_f32_e32 v69, v79, v245
	v_add_f32_e32 v68, v156, v68
	v_exp_f32_e32 v160, v69
	v_sub_f32_e32 v69, v80, v245
	v_add_f32_e32 v68, v157, v68
	v_exp_f32_e32 v161, v69
	v_sub_f32_e32 v69, v81, v245
	v_add_f32_e32 v68, v158, v68
	v_exp_f32_e32 v162, v69
	v_sub_f32_e32 v69, v82, v245
	v_add_f32_e32 v68, v159, v68
	v_exp_f32_e32 v163, v69
	v_sub_f32_e32 v69, v83, v245
	v_add_f32_e32 v68, v160, v68
	v_exp_f32_e32 v164, v69
	v_add_f32_e32 v68, v161, v68
	v_add_f32_e32 v68, v162, v68
	v_add_f32_e32 v68, v163, v68
	v_add_f32_e32 v241, v164, v68
	v_sub_f32_e32 v68, v148, v245
	v_exp_f32_e32 v194, v68
	ds_bpermute_b32 v242, v201, v241
	v_pk_mul_f32 v[82:83], v[50:51], v[194:195] op_sel_hi:[1,0]
	v_pk_mul_f32 v[80:81], v[48:49], v[194:195] op_sel_hi:[1,0]
	v_pk_mul_f32 v[78:79], v[46:47], v[194:195] op_sel_hi:[1,0]
	v_pk_mul_f32 v[76:77], v[44:45], v[194:195] op_sel_hi:[1,0]
	v_pk_mul_f32 v[74:75], v[42:43], v[194:195] op_sel_hi:[1,0]
	v_pk_mul_f32 v[72:73], v[40:41], v[194:195] op_sel_hi:[1,0]
	v_pk_mul_f32 v[70:71], v[38:39], v[194:195] op_sel_hi:[1,0]
	v_pk_mul_f32 v[68:69], v[36:37], v[194:195] op_sel_hi:[1,0]
	v_pk_mul_f32 v[98:99], v[66:67], v[194:195] op_sel_hi:[1,0]
	v_pk_mul_f32 v[96:97], v[64:65], v[194:195] op_sel_hi:[1,0]
	v_pk_mul_f32 v[94:95], v[62:63], v[194:195] op_sel_hi:[1,0]
	v_pk_mul_f32 v[92:93], v[60:61], v[194:195] op_sel_hi:[1,0]
	v_pk_mul_f32 v[90:91], v[58:59], v[194:195] op_sel_hi:[1,0]
	v_pk_mul_f32 v[88:89], v[56:57], v[194:195] op_sel_hi:[1,0]
	v_pk_mul_f32 v[86:87], v[54:55], v[194:195] op_sel_hi:[1,0]
	v_pk_mul_f32 v[84:85], v[52:53], v[194:195] op_sel_hi:[1,0]
	v_cvt_pk_bf16_f32 v36, v149, v150
	v_cvt_pk_bf16_f32 v37, v151, v152
	v_cvt_pk_bf16_f32 v38, v153, v154
	v_cvt_pk_bf16_f32 v39, v155, v156
	s_nop 1
	v_mfma_f32_32x32x16_bf16 v[68:83], v[144:147], v[36:39], v[68:83]
	v_mfma_f32_32x32x16_bf16 v[84:99], v[140:143], v[36:39], v[84:99]
	v_cvt_pk_bf16_f32 v36, v157, v158
	v_cvt_pk_bf16_f32 v37, v159, v160
	v_cvt_pk_bf16_f32 v38, v161, v162
	v_cvt_pk_bf16_f32 v39, v163, v164
	s_nop 1
	v_mfma_f32_32x32x16_bf16 v[68:83], v[136:139], v[36:39], v[68:83]
	v_mfma_f32_32x32x16_bf16 v[84:99], v[132:135], v[36:39], v[84:99]
	v_mul_lo_u32 v36, s56, v222
	v_add_u32_e32 v40, s11, v36
	v_max_i32_e32 v164, 0, v40
	v_lshl_add_u64 v[36:37], s[12:13], 0, v[164:165]
	v_lshlrev_b64 v[36:37], 7, v[36:37]
	s_waitcnt vmcnt(0)
	v_lshl_add_u64 v[38:39], v[180:181], 0, v[36:37]
	s_mov_b32 m0, s57
	v_add_u32_e32 v40, s6, v40
	global_load_lds_dwordx4 v[38:39], off
	v_lshl_add_u64 v[36:37], v[182:183], 0, v[36:37]
	s_mov_b32 m0, s7
	v_max_i32_e32 v164, 0, v40
	global_load_lds_dwordx4 v[36:37], off
	v_lshl_add_u64 v[36:37], s[12:13], 0, v[164:165]
	v_lshlrev_b64 v[36:37], 7, v[36:37]
	v_readlane_b32 s7, v254, 28
	v_lshl_add_u64 v[38:39], v[180:181], 0, v[36:37]
	s_mov_b32 m0, s7
	v_readlane_b32 s7, v254, 29
	v_add_u32_e32 v40, s6, v40
	global_load_lds_dwordx4 v[38:39], off
	v_lshl_add_u64 v[36:37], v[182:183], 0, v[36:37]
	s_mov_b32 m0, s7
	v_max_i32_e32 v164, 0, v40
	global_load_lds_dwordx4 v[36:37], off
	v_lshl_add_u64 v[36:37], s[12:13], 0, v[164:165]
	v_lshlrev_b64 v[36:37], 7, v[36:37]
	v_lshl_add_u64 v[38:39], v[180:181], 0, v[36:37]
	s_mov_b32 m0, s15
	v_lshl_add_u64 v[36:37], v[182:183], 0, v[36:37]
	global_load_lds_dwordx4 v[38:39], off
	s_mov_b32 m0, s17
	v_sub_u32_e32 v52, v199, v223
	global_load_lds_dwordx4 v[36:37], off
	v_add_u32_e32 v36, s6, v40
	v_max_i32_e32 v164, 0, v36
	v_lshl_add_u64 v[36:37], s[12:13], 0, v[164:165]
	v_lshlrev_b64 v[36:37], 7, v[36:37]
	v_lshl_add_u64 v[38:39], v[180:181], 0, v[36:37]
	s_mov_b32 m0, s21
	v_readlane_b32 s6, v254, 30
	global_load_lds_dwordx4 v[38:39], off
	v_lshl_add_u64 v[36:37], v[182:183], 0, v[36:37]
	s_mov_b32 m0, s6
	v_mov_b32_e32 v53, v224
	global_load_lds_dwordx4 v[36:37], off
	ds_read_b128 v[160:163], v225
	ds_read_b128 v[156:159], v226
	ds_read_b128 v[152:155], v227
	ds_read_b128 v[148:151], v228
	ds_read_b64_tr_b16 v[144:145], v229 offset:8192
	ds_read_b64_tr_b16 v[146:147], v229 offset:9216
	ds_read_b64_tr_b16 v[140:141], v229 offset:8256
	ds_read_b64_tr_b16 v[142:143], v229 offset:9280
	ds_read_b64_tr_b16 v[136:137], v229 offset:10240
	ds_read_b64_tr_b16 v[138:139], v229 offset:11264
	ds_read_b64_tr_b16 v[132:133], v229 offset:10304
	ds_read_b64_tr_b16 v[134:135], v229 offset:11328
	s_waitcnt lgkmcnt(0)
; __device__ __forceinline__ unsigned pk2(float lo, float hi) { return pg8::cvt_pk_bf16(lo, hi); }
; #define ATT_LOAD_Q(dst, J, set) do { const int qp_ = (J).pos0 + (32 * (set) + qc) * (J).d; _Pragma("unroll") for (int kk_ = 0; kk_ < 4; ++kk_) dst[kk_] = gld<bf16x8>(Qa + ((J).hb + (size_t)qp_) * 64 + 8 * h + 16 * kk_); } while (0)
; __device__ __forceinline__ void att_block(const bf16x8 (&kf)[4], const bf16x8 (&qf)[4], const bf16x8 (&va)[4], f32x16& o0, f32x16& o1, float& mrun, float& lrun, bool domask, int lo_, int hi_) {
;     ...
; #pragma unroll
;     for (int kk = 0; kk < 4; ++kk) st = __builtin_amdgcn_mfma_f32_32x32x16_bf16(kf[kk], qf[kk], st, 0, 0, 0);
;     if (domask) {
;         asm volatile("" : "+v"(lo_), "+v"(hi_));
; #pragma unroll
;         for (int i = 0; i < 16; ++i) { const int ci = (i & 3) + 8 * (i >> 2); st[i] = ((ci - lo_) | (hi_ - ci)) < 0 ? -INFINITY : st[i]; }
;     }
;     float bmax = -INFINITY;
; #pragma unroll
;     for (int i = 0; i < 16; ++i) bmax = fmaxf(bmax, st[i]);
;     bmax = fmaxf(bmax, __shfl_xor(bmax, 32));
;     const float mnew = fmaxf(mrun, bmax);
;     float lsum = 0.f;
; #pragma unroll
;     for (int i = 0; i < 16; ++i) { st[i] = __builtin_amdgcn_exp2f(st[i] - mnew); lsum += st[i]; }
;     lsum += __shfl_xor(lsum, 32);
;     const float alpha = __builtin_amdgcn_exp2f(mrun - mnew);
;     lrun = lrun * alpha + lsum; mrun = mnew;
; #pragma unroll
;     for (int i = 0; i < 16; ++i) { o0[i] *= alpha; o1[i] *= alpha; }
; #pragma unroll
;     for (int s = 0; s < 2; ++s) { v4u w; w.x = pk2(st[8 * s], st[8 * s + 1]); w.y = pk2(st[8 * s + 2], st[8 * s + 3]); w.z = pk2(st[8 * s + 4], st[8 * s + 5]); w.w = pk2(st[8 * s + 6], st[8 * s + 7]);
;         const bf16x8 pb = __builtin_bit_cast(bf16x8, w);
;         o0 = __builtin_amdgcn_mfma_f32_32x32x16_bf16(va[2 * s], pb, o0, 0, 0, 0);
;         o1 = __builtin_amdgcn_mfma_f32_32x32x16_bf16(va[2 * s + 1], pb, o1, 0, 0, 0); }
; __device__ __forceinline__ void att_phase(unsigned char* ws, LAS unsigned char* lds, int lane, int wave, int G) {
;     ...
;             if (kb <= 4) {
;                 att_block(kf, qfA, va, oA0, oA1, mA, lA, kb == 0 || kb == 4 || kminA > 32 * kb, mloA - 4 * h - 32 * kb, qc + 128 - 4 * h - 32 * kb);
;                 if (kb == 4 && hn) ATT_LOAD_Q(qfA, N, 0);
	v_mfma_f32_32x32x16_bf16 v[36:51], v[160:163], v[128:131], 0
	s_nop 0
	v_sub_u32_e32 v54, 0, v52
	v_or_b32_e32 v54, v53, v54
	v_cmp_lt_i32_e32 vcc, -1, v54
	v_sub_u32_e32 v54, 1, v52
	v_add_u32_e32 v55, -1, v53
	v_mfma_f32_32x32x16_bf16 v[36:51], v[156:159], v[124:127], v[36:51]
	v_or_b32_e32 v54, v54, v55
	v_add_u32_e32 v55, -2, v53
	v_mfma_f32_32x32x16_bf16 v[36:51], v[152:155], v[120:123], v[36:51]
	v_mfma_f32_32x32x16_bf16 v[36:51], v[148:151], v[116:119], v[36:51]
	s_nop 11
	v_cndmask_b32_e32 v36, v211, v36, vcc
	v_cmp_lt_i32_e32 vcc, -1, v54
	v_sub_u32_e32 v54, 2, v52
	v_or_b32_e32 v54, v54, v55
	v_cndmask_b32_e32 v37, v211, v37, vcc
	v_cmp_lt_i32_e32 vcc, -1, v54
	v_sub_u32_e32 v54, 3, v52
	v_add_u32_e32 v55, -3, v53
	v_or_b32_e32 v54, v54, v55
	v_cndmask_b32_e32 v38, v211, v38, vcc
	v_cmp_lt_i32_e32 vcc, -1, v54
	v_sub_u32_e32 v54, 8, v52
	v_add_u32_e32 v55, -8, v53
	v_or_b32_e32 v54, v54, v55
	v_cndmask_b32_e32 v39, v211, v39, vcc
	v_cmp_lt_i32_e32 vcc, -1, v54
	v_sub_u32_e32 v54, 9, v52
	v_add_u32_e32 v55, -9, v53
	v_or_b32_e32 v54, v54, v55
	v_cndmask_b32_e32 v40, v211, v40, vcc
	v_cmp_lt_i32_e32 vcc, -1, v54
	v_sub_u32_e32 v54, 10, v52
	v_add_u32_e32 v55, -10, v53
	v_or_b32_e32 v54, v54, v55
	v_cndmask_b32_e32 v41, v211, v41, vcc
	v_cmp_lt_i32_e32 vcc, -1, v54
	v_sub_u32_e32 v54, 11, v52
	v_add_u32_e32 v55, -11, v53
	v_or_b32_e32 v54, v54, v55
	v_cndmask_b32_e32 v42, v211, v42, vcc
	v_cmp_lt_i32_e32 vcc, -1, v54
	v_sub_u32_e32 v54, 16, v52
	v_add_u32_e32 v55, -16, v53
	v_or_b32_e32 v54, v54, v55
	v_cndmask_b32_e32 v43, v211, v43, vcc
	v_cmp_lt_i32_e32 vcc, -1, v54
	v_sub_u32_e32 v54, 17, v52
	v_subrev_u32_e32 v55, 17, v53
	v_or_b32_e32 v54, v54, v55
	v_cndmask_b32_e32 v44, v211, v44, vcc
	v_cmp_lt_i32_e32 vcc, -1, v54
	v_sub_u32_e32 v54, 18, v52
	v_subrev_u32_e32 v55, 18, v53
	v_or_b32_e32 v54, v54, v55
	v_cndmask_b32_e32 v45, v211, v45, vcc
	v_cmp_lt_i32_e32 vcc, -1, v54
	v_sub_u32_e32 v54, 19, v52
	v_subrev_u32_e32 v55, 19, v53
	v_or_b32_e32 v54, v54, v55
	v_cndmask_b32_e32 v46, v211, v46, vcc
	v_cmp_lt_i32_e32 vcc, -1, v54
	v_sub_u32_e32 v54, 24, v52
	v_subrev_u32_e32 v55, 24, v53
	v_or_b32_e32 v54, v54, v55
	v_cndmask_b32_e32 v47, v211, v47, vcc
	v_cmp_lt_i32_e32 vcc, -1, v54
	v_sub_u32_e32 v54, 25, v52
	v_subrev_u32_e32 v55, 25, v53
	v_or_b32_e32 v54, v54, v55
	v_cndmask_b32_e32 v48, v211, v48, vcc
	v_cmp_lt_i32_e32 vcc, -1, v54
	v_sub_u32_e32 v54, 26, v52
	v_subrev_u32_e32 v55, 26, v53
	v_or_b32_e32 v54, v54, v55
	v_sub_u32_e32 v52, 27, v52
	v_subrev_u32_e32 v53, 27, v53
	v_cndmask_b32_e32 v49, v211, v49, vcc
	v_cmp_lt_i32_e32 vcc, -1, v54
	v_or_b32_e32 v52, v52, v53
	s_nop 0
	v_cndmask_b32_e32 v50, v211, v50, vcc
	v_cmp_lt_i32_e32 vcc, -1, v52
	v_max3_f32 v52, v36, s58, v37
	v_max3_f32 v52, v52, v38, v39
	v_max3_f32 v52, v52, v40, v41
	v_max3_f32 v52, v52, v42, v43
	v_max3_f32 v52, v52, v44, v45
	v_max3_f32 v52, v52, v46, v47
	v_cndmask_b32_e32 v51, v211, v51, vcc
	v_max3_f32 v52, v52, v48, v49
	v_max3_f32 v52, v52, v50, v51
	ds_bpermute_b32 v53, v201, v52
	s_andn2_b64 vcc, exec, s[2:3]
	s_waitcnt lgkmcnt(0)
	v_max3_f32 v200, v202, v52, v53
	v_sub_f32_e32 v36, v36, v200
	v_exp_f32_e32 v164, v36
	v_sub_f32_e32 v37, v37, v200
	v_exp_f32_e32 v166, v37
	v_sub_f32_e32 v37, v38, v200
	v_exp_f32_e32 v167, v37
	v_sub_f32_e32 v37, v39, v200
	v_exp_f32_e32 v199, v37
	v_sub_f32_e32 v37, v40, v200
	v_add_f32_e32 v36, 0, v164
	v_exp_f32_e32 v248, v37
	v_sub_f32_e32 v37, v41, v200
	v_add_f32_e32 v36, v166, v36
	v_exp_f32_e32 v249, v37
	v_sub_f32_e32 v37, v42, v200
	v_add_f32_e32 v36, v167, v36
	v_exp_f32_e32 v250, v37
	v_sub_f32_e32 v37, v43, v200
	v_add_f32_e32 v36, v199, v36
	v_exp_f32_e32 v251, v37
	v_sub_f32_e32 v37, v44, v200
	v_add_f32_e32 v36, v248, v36
	v_exp_f32_e32 v252, v37
	v_sub_f32_e32 v37, v45, v200
	v_add_f32_e32 v36, v249, v36
	v_exp_f32_e32 v203, v37
	v_sub_f32_e32 v37, v46, v200
	v_add_f32_e32 v36, v250, v36
	v_exp_f32_e32 v168, v37
	v_sub_f32_e32 v37, v47, v200
	v_add_f32_e32 v36, v251, v36
	v_exp_f32_e32 v169, v37
	v_sub_f32_e32 v37, v48, v200
	v_add_f32_e32 v36, v252, v36
	v_exp_f32_e32 v212, v37
	v_sub_f32_e32 v37, v49, v200
	v_add_f32_e32 v36, v203, v36
	v_exp_f32_e32 v209, v37
	v_sub_f32_e32 v37, v50, v200
	v_add_f32_e32 v36, v168, v36
	v_exp_f32_e32 v197, v37
	v_sub_f32_e32 v37, v51, v200
	v_add_f32_e32 v36, v169, v36
	v_exp_f32_e32 v195, v37
	v_add_f32_e32 v36, v212, v36
	v_add_f32_e32 v36, v209, v36
	v_add_f32_e32 v36, v197, v36
	v_add_f32_e32 v246, v195, v36
	v_sub_f32_e32 v36, v202, v200
	v_exp_f32_e32 v202, v36
	ds_bpermute_b32 v247, v201, v246
	v_pk_mul_f32 v[66:67], v[18:19], v[202:203] op_sel_hi:[1,0]
	v_pk_mul_f32 v[64:65], v[16:17], v[202:203] op_sel_hi:[1,0]
	v_pk_mul_f32 v[62:63], v[14:15], v[202:203] op_sel_hi:[1,0]
	v_pk_mul_f32 v[60:61], v[12:13], v[202:203] op_sel_hi:[1,0]
	v_pk_mul_f32 v[58:59], v[10:11], v[202:203] op_sel_hi:[1,0]
	v_pk_mul_f32 v[56:57], v[8:9], v[202:203] op_sel_hi:[1,0]
	v_pk_mul_f32 v[54:55], v[6:7], v[202:203] op_sel_hi:[1,0]
	v_pk_mul_f32 v[52:53], v[4:5], v[202:203] op_sel_hi:[1,0]
	v_pk_mul_f32 v[50:51], v[34:35], v[202:203] op_sel_hi:[1,0]
	v_pk_mul_f32 v[48:49], v[32:33], v[202:203] op_sel_hi:[1,0]
	v_pk_mul_f32 v[46:47], v[30:31], v[202:203] op_sel_hi:[1,0]
	v_pk_mul_f32 v[44:45], v[28:29], v[202:203] op_sel_hi:[1,0]
	v_pk_mul_f32 v[42:43], v[26:27], v[202:203] op_sel_hi:[1,0]
	v_pk_mul_f32 v[40:41], v[24:25], v[202:203] op_sel_hi:[1,0]
	v_pk_mul_f32 v[38:39], v[22:23], v[202:203] op_sel_hi:[1,0]
	v_pk_mul_f32 v[36:37], v[20:21], v[202:203] op_sel_hi:[1,0]
	v_cvt_pk_bf16_f32 v4, v164, v166
	v_cvt_pk_bf16_f32 v5, v167, v199
	v_cvt_pk_bf16_f32 v6, v248, v249
	v_cvt_pk_bf16_f32 v7, v250, v251
	s_nop 1
	v_mfma_f32_32x32x16_bf16 v[52:67], v[144:147], v[4:7], v[52:67]
	v_mfma_f32_32x32x16_bf16 v[36:51], v[140:143], v[4:7], v[36:51]
	v_cvt_pk_bf16_f32 v4, v252, v203
	v_cvt_pk_bf16_f32 v5, v168, v169
	v_cvt_pk_bf16_f32 v6, v212, v209
	v_cvt_pk_bf16_f32 v7, v197, v195
	s_nop 1
	v_mfma_f32_32x32x16_bf16 v[52:67], v[136:139], v[4:7], v[52:67]
	v_mfma_f32_32x32x16_bf16 v[36:51], v[132:135], v[4:7], v[36:51]
	v_cndmask_b32_e64 v4, 0, 1, s[2:3]
	v_cmp_ne_u32_e64 s[6:7], 1, v4
	s_cbranch_vccnz .LBB0_92
	v_ashrrev_i32_e32 v199, 31, v198
	v_lshl_add_u64 v[4:5], s[0:1], 0, v[198:199]
	v_lshlrev_b64 v[4:5], 7, v[4:5]
	v_lshl_add_u64 v[4:5], v[186:187], 0, v[4:5]
	global_load_dwordx4 v[128:131], v[4:5], off
	global_load_dwordx4 v[124:127], v[4:5], off offset:32
	global_load_dwordx4 v[120:123], v[4:5], off offset:64
	global_load_dwordx4 v[116:119], v[4:5], off offset:96

; #define LAS __attribute__((address_space(3)))
; __device__ __forceinline__ void att_block(const bf16x8 (&kf)[4], const bf16x8 (&qf)[4], const bf16x8 (&va)[4], f32x16& o0, f32x16& o1, float& mrun, float& lrun, bool domask, int lo_, int hi_) {
;     f32x16 st;
; #pragma unroll
;     for (int i = 0; i < 16; ++i) st[i] = 0.f;
; #pragma unroll
;     for (int kk = 0; kk < 4; ++kk) st = __builtin_amdgcn_mfma_f32_32x32x16_bf16(kf[kk], qf[kk], st, 0, 0, 0);
;     if (domask) {
;         asm volatile("" : "+v"(lo_), "+v"(hi_));
; #pragma unroll
;         for (int i = 0; i < 16; ++i) { const int ci = (i & 3) + 8 * (i >> 2); st[i] = ((ci - lo_) | (hi_ - ci)) < 0 ? -INFINITY : st[i]; }
;     }
;     float bmax = -INFINITY;
; #pragma unroll
;     for (int i = 0; i < 16; ++i) bmax = fmaxf(bmax, st[i]);
;     bmax = fmaxf(bmax, __shfl_xor(bmax, 32));
;     const float mnew = fmaxf(mrun, bmax);
;     float lsum = 0.f;
; #pragma unroll
;     for (int i = 0; i < 16; ++i) { st[i] = __builtin_amdgcn_exp2f(st[i] - mnew); lsum += st[i]; }
;     lsum += __shfl_xor(lsum, 32);
;     const float alpha = __builtin_amdgcn_exp2f(mrun - mnew);
;     lrun = lrun * alpha + lsum; mrun = mnew;
; #pragma unroll
;     for (int i = 0; i < 16; ++i) { o0[i] *= alpha; o1[i] *= alpha; }
; #pragma unroll
;     for (int s = 0; s < 2; ++s) { v4u w; w.x = pk2(st[8 * s], st[8 * s + 1]); w.y = pk2(st[8 * s + 2], st[8 * s + 3]); w.z = pk2(st[8 * s + 4], st[8 * s + 5]); w.w = pk2(st[8 * s + 6], st[8 * s + 7]);
;         const bf16x8 pb = __builtin_bit_cast(bf16x8, w);
;         o0 = __builtin_amdgcn_mfma_f32_32x32x16_bf16(va[2 * s], pb, o0, 0, 0, 0);
;         o1 = __builtin_amdgcn_mfma_f32_32x32x16_bf16(va[2 * s + 1], pb, o1, 0, 0, 0); }
; __device__ __forceinline__ void att_phase(unsigned char* ws, LAS unsigned char* lds, int lane, int wave, int G) {
;     ...
;             bf16x8 kf[4], va[4];
; #pragma unroll
;             for (int kk = 0; kk < 4; ++kk) kf[kk] = *(LAS const bf16x8*)(kfb + sb * 4096 + (((2 * kk + h) ^ (qc & 7)) << 4));
;             LAS const unsigned char* trs = trb + 8192 + sb * 4096;
; #pragma unroll
;             for (int s = 0; s < 2; ++s) {
;                 const s16x4 lo0 = vtr(trs + (16 * s) * VP), hi0 = vtr(trs + (16 * s + 8) * VP);
;                 const s16x4 lo1 = vtr(trs + (16 * s) * VP + 64), hi1 = vtr(trs + (16 * s + 8) * VP + 64);
.LBB0_96:
	ds_read_b128 v[68:71], v225 offset:4096
	ds_read_b128 v[132:135], v226 offset:4096
	ds_read_b128 v[136:139], v227 offset:4096
	ds_read_b128 v[140:143], v228 offset:4096
	ds_read_b64_tr_b16 v[92:93], v229 offset:12288
	ds_read_b64_tr_b16 v[94:95], v229 offset:13312
	ds_read_b64_tr_b16 v[86:87], v229 offset:13376
	ds_read_b64_tr_b16 v[84:85], v229 offset:12352
	s_waitcnt lgkmcnt(0)
	v_mfma_f32_32x32x16_bf16 v[68:83], v[68:71], v[112:115], 0
	v_sub_u32_e32 v144, v237, v223
	v_mov_b32_e32 v145, v224
	ds_read_b64_tr_b16 v[96:97], v229 offset:14336
	ds_read_b64_tr_b16 v[98:99], v229 offset:15360
	ds_read_b64_tr_b16 v[90:91], v229 offset:15424
	ds_read_b64_tr_b16 v[88:89], v229 offset:14400
	s_mov_b32 s14, 0xff800000
	v_add_u32_e32 v146, -2, v145
	v_sub_u32_e32 v147, 3, v144
	v_mfma_f32_32x32x16_bf16 v[68:83], v[132:135], v[108:111], v[68:83]
	v_sub_u32_e32 v132, 0, v144
	v_sub_u32_e32 v133, 1, v144
	v_add_u32_e32 v134, -1, v145
	v_or_b32_e32 v132, v145, v132
	v_sub_u32_e32 v135, 2, v144
	v_or_b32_e32 v133, v133, v134
	v_cmp_lt_i32_e32 vcc, -1, v132
	v_mfma_f32_32x32x16_bf16 v[68:83], v[136:139], v[104:107], v[68:83]
	v_add_u32_e32 v152, -3, v145
	v_or_b32_e32 v134, v135, v146
	v_sub_u32_e32 v136, 8, v144
	v_add_u32_e32 v137, -8, v145
	v_or_b32_e32 v135, v147, v152
	v_or_b32_e32 v136, v136, v137
	v_sub_u32_e32 v132, 9, v144
	v_mfma_f32_32x32x16_bf16 v[68:83], v[140:143], v[100:103], v[68:83]
	s_nop 11
	v_cndmask_b32_e32 v68, v211, v68, vcc
	v_cmp_lt_i32_e32 vcc, -1, v133
	v_add_u32_e32 v133, -9, v145
	v_or_b32_e32 v132, v132, v133
	v_cndmask_b32_e32 v69, v211, v69, vcc
	v_cmp_lt_i32_e32 vcc, -1, v134
	v_add_u32_e32 v133, -10, v145
	s_nop 0
	v_cndmask_b32_e32 v70, v211, v70, vcc
	v_cmp_lt_i32_e32 vcc, -1, v135
	s_nop 1
	v_cndmask_b32_e32 v71, v211, v71, vcc
	v_cmp_lt_i32_e32 vcc, -1, v136
	s_nop 1
	v_cndmask_b32_e32 v72, v211, v72, vcc
	v_cmp_lt_i32_e32 vcc, -1, v132
	v_sub_u32_e32 v132, 10, v144
	v_or_b32_e32 v132, v132, v133
	v_cndmask_b32_e32 v73, v211, v73, vcc
	v_cmp_lt_i32_e32 vcc, -1, v132
	v_sub_u32_e32 v132, 11, v144
	v_add_u32_e32 v133, -11, v145
	v_or_b32_e32 v132, v132, v133
	v_cndmask_b32_e32 v74, v211, v74, vcc
	v_cmp_lt_i32_e32 vcc, -1, v132
	v_sub_u32_e32 v132, 16, v144
	v_add_u32_e32 v133, -16, v145
	v_or_b32_e32 v132, v132, v133
	v_cndmask_b32_e32 v75, v211, v75, vcc
	v_cmp_lt_i32_e32 vcc, -1, v132
	v_subrev_u32_e32 v133, 17, v145
	s_nop 0
	v_cndmask_b32_e32 v132, v211, v76, vcc
	v_sub_u32_e32 v76, 17, v144
	v_or_b32_e32 v76, v76, v133
	v_cmp_lt_i32_e32 vcc, -1, v76
	v_sub_u32_e32 v76, 18, v144
	v_subrev_u32_e32 v133, 18, v145
	v_or_b32_e32 v76, v76, v133
	v_cndmask_b32_e32 v77, v211, v77, vcc
	v_cmp_lt_i32_e32 vcc, -1, v76
	v_sub_u32_e32 v76, 19, v144
	v_subrev_u32_e32 v133, 19, v145
	v_or_b32_e32 v76, v76, v133
	v_cndmask_b32_e32 v78, v211, v78, vcc
	v_cmp_lt_i32_e32 vcc, -1, v76
	v_sub_u32_e32 v76, 24, v144
	v_subrev_u32_e32 v133, 24, v145
	v_or_b32_e32 v76, v76, v133
	v_cndmask_b32_e32 v79, v211, v79, vcc
	v_cmp_lt_i32_e32 vcc, -1, v76
	v_sub_u32_e32 v76, 25, v144
	v_subrev_u32_e32 v133, 25, v145
	v_or_b32_e32 v76, v76, v133
	v_cndmask_b32_e32 v80, v211, v80, vcc
	v_cmp_lt_i32_e32 vcc, -1, v76
	v_sub_u32_e32 v76, 26, v144
	v_subrev_u32_e32 v133, 26, v145
	v_or_b32_e32 v76, v76, v133
	v_cndmask_b32_e32 v81, v211, v81, vcc
	v_cmp_lt_i32_e32 vcc, -1, v76
	v_sub_u32_e32 v76, 27, v144
	v_subrev_u32_e32 v133, 27, v145
	v_or_b32_e32 v76, v76, v133
	v_cndmask_b32_e32 v82, v211, v82, vcc
	v_cmp_lt_i32_e32 vcc, -1, v76
	v_max3_f32 v76, v68, s14, v69
	v_max3_f32 v76, v76, v70, v71
	v_max3_f32 v76, v76, v72, v73
	v_max3_f32 v76, v76, v74, v75
	v_max3_f32 v76, v76, v132, v77
	v_max3_f32 v76, v76, v78, v79
	v_cndmask_b32_e32 v83, v211, v83, vcc
	v_max3_f32 v76, v76, v80, v81
	v_max3_f32 v76, v76, v82, v83
	ds_bpermute_b32 v133, v201, v76
	s_and_b64 vcc, exec, s[6:7]
	s_waitcnt lgkmcnt(0)
	v_max3_f32 v76, v151, v76, v133
	v_sub_f32_e32 v68, v68, v76
	v_exp_f32_e32 v68, v68
	v_sub_f32_e32 v69, v69, v76
	v_exp_f32_e32 v69, v69
	v_sub_f32_e32 v70, v70, v76
	v_exp_f32_e32 v70, v70
	v_sub_f32_e32 v71, v71, v76
	v_exp_f32_e32 v71, v71
	v_sub_f32_e32 v72, v72, v76
	v_add_f32_e32 v133, 0, v68
	v_exp_f32_e32 v72, v72
	v_sub_f32_e32 v73, v73, v76
	v_add_f32_e32 v133, v69, v133
	v_exp_f32_e32 v73, v73
	v_sub_f32_e32 v74, v74, v76
	v_add_f32_e32 v133, v70, v133
	v_exp_f32_e32 v74, v74
	v_sub_f32_e32 v75, v75, v76
	v_add_f32_e32 v133, v71, v133
	v_exp_f32_e32 v75, v75
	v_sub_f32_e32 v132, v132, v76
	v_add_f32_e32 v133, v72, v133
	v_exp_f32_e32 v132, v132
	v_sub_f32_e32 v77, v77, v76
	v_add_f32_e32 v133, v73, v133
	v_exp_f32_e32 v77, v77
	v_sub_f32_e32 v78, v78, v76
	v_add_f32_e32 v133, v74, v133
	v_exp_f32_e32 v134, v78
	v_add_f32_e32 v78, v75, v133
	v_add_f32_e32 v78, v132, v78
	v_add_f32_e32 v78, v77, v78
	v_add_f32_e32 v133, v134, v78
	v_sub_f32_e32 v78, v79, v76
	v_exp_f32_e32 v79, v78
	v_sub_f32_e32 v78, v80, v76
	v_exp_f32_e32 v80, v78
	v_sub_f32_e32 v78, v151, v76
	v_exp_f32_e32 v78, v78
	v_cvt_pk_bf16_f32 v68, v68, v69
	v_cvt_pk_bf16_f32 v69, v70, v71
	v_cvt_pk_bf16_f32 v70, v72, v73
	v_pk_mul_f32 v[34:35], v[34:35], v[78:79] op_sel_hi:[1,0]
	v_pk_mul_f32 v[32:33], v[32:33], v[78:79] op_sel_hi:[1,0]
	v_pk_mul_f32 v[30:31], v[30:31], v[78:79] op_sel_hi:[1,0]
	v_pk_mul_f32 v[28:29], v[28:29], v[78:79] op_sel_hi:[1,0]
	v_pk_mul_f32 v[26:27], v[26:27], v[78:79] op_sel_hi:[1,0]
	v_pk_mul_f32 v[24:25], v[24:25], v[78:79] op_sel_hi:[1,0]
	v_pk_mul_f32 v[22:23], v[22:23], v[78:79] op_sel_hi:[1,0]
	v_pk_mul_f32 v[20:21], v[20:21], v[78:79] op_sel_hi:[1,0]
	v_pk_mul_f32 v[18:19], v[18:19], v[78:79] op_sel_hi:[1,0]
	v_cvt_pk_bf16_f32 v71, v74, v75
	v_pk_mul_f32 v[16:17], v[16:17], v[78:79] op_sel_hi:[1,0]
	v_pk_mul_f32 v[14:15], v[14:15], v[78:79] op_sel_hi:[1,0]
	v_pk_mul_f32 v[12:13], v[12:13], v[78:79] op_sel_hi:[1,0]
	v_pk_mul_f32 v[10:11], v[10:11], v[78:79] op_sel_hi:[1,0]
	v_pk_mul_f32 v[8:9], v[8:9], v[78:79] op_sel_hi:[1,0]
	v_pk_mul_f32 v[6:7], v[6:7], v[78:79] op_sel_hi:[1,0]
	v_pk_mul_f32 v[4:5], v[4:5], v[78:79] op_sel_hi:[1,0]
	v_mfma_f32_32x32x16_bf16 v[20:35], v[92:95], v[68:71], v[20:35]
	v_sub_f32_e32 v81, v81, v76
	v_sub_f32_e32 v82, v82, v76
	v_exp_f32_e32 v81, v81
	v_exp_f32_e32 v72, v82
	v_add_f32_e32 v74, v79, v133
	v_add_f32_e32 v74, v80, v74
	v_add_f32_e32 v74, v81, v74
	v_mfma_f32_32x32x16_bf16 v[4:19], v[84:87], v[68:71], v[4:19]
	v_sub_f32_e32 v68, v83, v76
	v_exp_f32_e32 v73, v68
	v_cvt_pk_bf16_f32 v68, v132, v77
	v_cvt_pk_bf16_f32 v69, v134, v79
	v_cvt_pk_bf16_f32 v70, v80, v81
	v_cvt_pk_bf16_f32 v71, v72, v73
	v_add_f32_e32 v72, v72, v74
	v_add_f32_e32 v77, v73, v72
	v_mfma_f32_32x32x16_bf16 v[20:35], v[96:99], v[68:71], v[20:35]
	ds_bpermute_b32 v79, v201, v77
	v_mfma_f32_32x32x16_bf16 v[4:19], v[88:91], v[68:71], v[4:19]
	s_cbranch_vccnz .LBB0_98
; #define ATT_LOAD_Q(dst, J, set) do { const int qp_ = (J).pos0 + (32 * (set) + qc) * (J).d; _Pragma("unroll") for (int kk_ = 0; kk_ < 4; ++kk_) dst[kk_] = gld<bf16x8>(Qa + ((J).hb + (size_t)qp_) * 64 + 8 * h + 16 * kk_); } while (0)
; __device__ __forceinline__ void att_phase(unsigned char* ws, LAS unsigned char* lds, int lane, int wave, int G) {
;     ...
;                 if (kb == 5 && hn) ATT_LOAD_Q(qfB, N, 1);
	v_lshl_add_u32 v68, s52, 5, v198
	v_ashrrev_i32_e32 v69, 31, v68
	v_lshl_add_u64 v[68:69], s[0:1], 0, v[68:69]
	v_lshlrev_b64 v[68:69], 7, v[68:69]
	v_lshl_add_u64 v[68:69], v[186:187], 0, v[68:69]
	global_load_dwordx4 v[112:115], v[68:69], off
	global_load_dwordx4 v[108:111], v[68:69], off offset:32
	global_load_dwordx4 v[104:107], v[68:69], off offset:64
	global_load_dwordx4 v[100:103], v[68:69], off offset:96
